# back-edge SALU hoist: loop counter / pointer / compare ops of the 7 bf16 K-loops moved into the MFMA shadow, loop path is branch only
# baseline (speedup 1.0000x reference)
.LBB0_170:
	ds_read_b128 v[128:131], v168
	ds_read_b128 v[132:135], v168 offset:1024
	ds_read_b128 v[136:139], v168 offset:2048
	ds_read_b128 v[140:143], v168 offset:3072
	ds_read_b128 v[152:155], v169
	ds_read_b128 v[156:159], v169 offset:1024
	ds_read_b128 v[160:163], v169 offset:2048
	ds_read_b128 v[172:175], v169 offset:3072
	s_add_u32 s2, s52, 0x10000
	s_addc_u32 s3, s53, 0
	s_cmp_eq_u32 s88, 60
	s_cselect_b32 s48, s82, s2
	s_cselect_b32 s49, s39, s3
	s_cselect_b32 s90, s83, s54
	s_cselect_b32 s91, s15, s55
	s_add_u32 s80, s48, 0x8000
	s_addc_u32 s81, s49, 0
	ds_read_b128 v[176:179], v170
	ds_read_b128 v[180:183], v170 offset:1024
	ds_read_b128 v[184:187], v170 offset:2048
	ds_read_b128 v[188:191], v170 offset:3072
	ds_read_b128 v[192:195], v170 offset:4096
	ds_read_b128 v[196:199], v170 offset:5120
	ds_read_b128 v[200:203], v170 offset:6144
	ds_read_b128 v[204:207], v170 offset:7168
	s_add_u32 s92, s52, 0xc000
	s_addc_u32 s93, s53, 0
	s_mov_b32 m0, s72
	s_nop 0
	global_load_lds_dwordx4 v166, s[92:93]
	s_add_u32 s52, s52, 0xe000
	s_addc_u32 s53, s53, 0
	s_mov_b32 m0, s75
	s_nop 0
	global_load_lds_dwordx4 v166, s[52:53]
	s_waitcnt vmcnt(8)
	s_waitcnt lgkmcnt(0)
	s_add_u32 s92, s90, 0x8000
	s_addc_u32 s93, s91, 0
	s_barrier
	s_setprio 1
	s_waitcnt lgkmcnt(7)
	s_waitcnt lgkmcnt(0)
	v_mfma_f32_16x16x32_bf16 v[112:115], v[128:131], v[176:179], v[112:115]
	v_mfma_f32_16x16x32_bf16 v[112:115], v[132:135], v[180:183], v[112:115]
	v_mfma_f32_16x16x32_bf16 v[96:99], v[128:131], v[184:187], v[96:99]
	v_mfma_f32_16x16x32_bf16 v[96:99], v[132:135], v[188:191], v[96:99]
	v_mfma_f32_16x16x32_bf16 v[80:83], v[128:131], v[192:195], v[80:83]
	v_mfma_f32_16x16x32_bf16 v[80:83], v[132:135], v[196:199], v[80:83]
	v_mfma_f32_16x16x32_bf16 v[60:63], v[128:131], v[200:203], v[60:63]
	v_mfma_f32_16x16x32_bf16 v[60:63], v[132:135], v[204:207], v[60:63]
	v_mfma_f32_16x16x32_bf16 v[72:75], v[136:139], v[200:203], v[72:75]
	v_mfma_f32_16x16x32_bf16 v[72:75], v[140:143], v[204:207], v[72:75]
	v_mfma_f32_16x16x32_bf16 v[88:91], v[136:139], v[192:195], v[88:91]
	v_mfma_f32_16x16x32_bf16 v[88:91], v[140:143], v[196:199], v[88:91]
	v_mfma_f32_16x16x32_bf16 v[104:107], v[136:139], v[184:187], v[104:107]
	v_mfma_f32_16x16x32_bf16 v[104:107], v[140:143], v[188:191], v[104:107]
	v_mfma_f32_16x16x32_bf16 v[120:123], v[136:139], v[176:179], v[120:123]
	v_mfma_f32_16x16x32_bf16 v[120:123], v[140:143], v[180:183], v[120:123]
	s_setprio 0
	s_setprio 1
	s_waitcnt lgkmcnt(0)
	v_mfma_f32_16x16x32_bf16 v[116:119], v[152:155], v[176:179], v[116:119]
	v_mfma_f32_16x16x32_bf16 v[116:119], v[156:159], v[180:183], v[116:119]
	v_mfma_f32_16x16x32_bf16 v[100:103], v[152:155], v[184:187], v[100:103]
	v_mfma_f32_16x16x32_bf16 v[100:103], v[156:159], v[188:191], v[100:103]
	v_mfma_f32_16x16x32_bf16 v[84:87], v[152:155], v[192:195], v[84:87]
	v_mfma_f32_16x16x32_bf16 v[84:87], v[156:159], v[196:199], v[84:87]
	v_mfma_f32_16x16x32_bf16 v[68:71], v[152:155], v[200:203], v[68:71]
	v_mfma_f32_16x16x32_bf16 v[68:71], v[156:159], v[204:207], v[68:71]
	v_mfma_f32_16x16x32_bf16 v[76:79], v[160:163], v[200:203], v[76:79]
	v_mfma_f32_16x16x32_bf16 v[76:79], v[172:175], v[204:207], v[76:79]
	v_mfma_f32_16x16x32_bf16 v[92:95], v[160:163], v[192:195], v[92:95]
	v_mfma_f32_16x16x32_bf16 v[92:95], v[172:175], v[196:199], v[92:95]
	v_mfma_f32_16x16x32_bf16 v[108:111], v[160:163], v[184:187], v[108:111]
	v_mfma_f32_16x16x32_bf16 v[108:111], v[172:175], v[188:191], v[108:111]
	v_mfma_f32_16x16x32_bf16 v[124:127], v[160:163], v[176:179], v[124:127]
	s_barrier
	v_mfma_f32_16x16x32_bf16 v[124:127], v[172:175], v[180:183], v[124:127]
	s_setprio 0
	s_add_u32 s52, s90, 0x2000
	ds_read_b128 v[176:179], v170 offset:16384
	ds_read_b128 v[180:183], v170 offset:17408
	ds_read_b128 v[184:187], v170 offset:18432
	ds_read_b128 v[188:191], v170 offset:19456
	ds_read_b128 v[192:195], v170 offset:20480
	ds_read_b128 v[196:199], v170 offset:21504
	ds_read_b128 v[200:203], v170 offset:22528
	ds_read_b128 v[204:207], v170 offset:23552
	s_mov_b32 m0, s45
	s_nop 0
	global_load_lds_dwordx4 v166, s[90:91]
	s_addc_u32 s53, s91, 0
	s_mov_b32 m0, s47
	s_nop 0
	global_load_lds_dwordx4 v166, s[52:53]
	s_add_u32 s52, s90, 0x4000
	s_addc_u32 s53, s91, 0
	s_mov_b32 m0, s58
	s_nop 0
	global_load_lds_dwordx4 v166, s[52:53]
	s_add_u32 s52, s90, 0x6000
	s_addc_u32 s53, s91, 0
	s_mov_b32 m0, s59
	s_nop 0
	global_load_lds_dwordx4 v166, s[52:53]
	s_add_u32 s52, s48, 0x2000
	s_mov_b32 m0, s57
	s_nop 0
	global_load_lds_dwordx4 v166, s[48:49]
	s_addc_u32 s53, s49, 0
	s_mov_b32 m0, s60
	s_nop 0
	global_load_lds_dwordx4 v166, s[52:53]
	s_waitcnt vmcnt(8)
	s_waitcnt lgkmcnt(0)
	s_barrier
	s_setprio 1
	s_waitcnt lgkmcnt(7)
	s_waitcnt lgkmcnt(0)
	v_mfma_f32_16x16x32_bf16 v[48:51], v[128:131], v[176:179], v[48:51]
	v_mfma_f32_16x16x32_bf16 v[48:51], v[132:135], v[180:183], v[48:51]
	v_mfma_f32_16x16x32_bf16 v[32:35], v[128:131], v[184:187], v[32:35]
	v_mfma_f32_16x16x32_bf16 v[32:35], v[132:135], v[188:191], v[32:35]
	v_mfma_f32_16x16x32_bf16 v[16:19], v[128:131], v[192:195], v[16:19]
	v_mfma_f32_16x16x32_bf16 v[16:19], v[132:135], v[196:199], v[16:19]
	v_mfma_f32_16x16x32_bf16 v[0:3], v[128:131], v[200:203], v[0:3]
	v_mfma_f32_16x16x32_bf16 v[0:3], v[132:135], v[204:207], v[0:3]
	v_mfma_f32_16x16x32_bf16 v[8:11], v[136:139], v[200:203], v[8:11]
	v_mfma_f32_16x16x32_bf16 v[8:11], v[140:143], v[204:207], v[8:11]
	v_mfma_f32_16x16x32_bf16 v[24:27], v[136:139], v[192:195], v[24:27]
	v_mfma_f32_16x16x32_bf16 v[24:27], v[140:143], v[196:199], v[24:27]
	v_mfma_f32_16x16x32_bf16 v[40:43], v[136:139], v[184:187], v[40:43]
	v_mfma_f32_16x16x32_bf16 v[40:43], v[140:143], v[188:191], v[40:43]
	v_mfma_f32_16x16x32_bf16 v[56:59], v[136:139], v[176:179], v[56:59]
	v_mfma_f32_16x16x32_bf16 v[56:59], v[140:143], v[180:183], v[56:59]
	s_setprio 0
	s_setprio 1
	s_waitcnt lgkmcnt(0)
	v_mfma_f32_16x16x32_bf16 v[52:55], v[152:155], v[176:179], v[52:55]
	v_mfma_f32_16x16x32_bf16 v[52:55], v[156:159], v[180:183], v[52:55]
	v_mfma_f32_16x16x32_bf16 v[36:39], v[152:155], v[184:187], v[36:39]
	v_mfma_f32_16x16x32_bf16 v[36:39], v[156:159], v[188:191], v[36:39]
	v_mfma_f32_16x16x32_bf16 v[20:23], v[152:155], v[192:195], v[20:23]
	v_mfma_f32_16x16x32_bf16 v[20:23], v[156:159], v[196:199], v[20:23]
	v_mfma_f32_16x16x32_bf16 v[4:7], v[152:155], v[200:203], v[4:7]
	v_mfma_f32_16x16x32_bf16 v[4:7], v[156:159], v[204:207], v[4:7]
	v_mfma_f32_16x16x32_bf16 v[12:15], v[160:163], v[200:203], v[12:15]
	v_mfma_f32_16x16x32_bf16 v[12:15], v[172:175], v[204:207], v[12:15]
	v_mfma_f32_16x16x32_bf16 v[28:31], v[160:163], v[192:195], v[28:31]
	v_mfma_f32_16x16x32_bf16 v[28:31], v[172:175], v[196:199], v[28:31]
	v_mfma_f32_16x16x32_bf16 v[44:47], v[160:163], v[184:187], v[44:47]
	v_mfma_f32_16x16x32_bf16 v[44:47], v[172:175], v[188:191], v[44:47]
	v_mfma_f32_16x16x32_bf16 v[64:67], v[160:163], v[176:179], v[64:67]
	s_barrier
	v_mfma_f32_16x16x32_bf16 v[64:67], v[172:175], v[180:183], v[64:67]
	s_setprio 0
	ds_read_b128 v[128:131], v148
	ds_read_b128 v[132:135], v148 offset:1024
	ds_read_b128 v[136:139], v148 offset:2048
	ds_read_b128 v[140:143], v148 offset:3072
	ds_read_b128 v[152:155], v150
	ds_read_b128 v[156:159], v150 offset:1024
	ds_read_b128 v[160:163], v150 offset:2048
	ds_read_b128 v[172:175], v150 offset:3072
	ds_read_b128 v[176:179], v170 offset:32768
	ds_read_b128 v[180:183], v170 offset:33792
	ds_read_b128 v[184:187], v170 offset:34816
	ds_read_b128 v[188:191], v170 offset:35840
	ds_read_b128 v[192:195], v170 offset:36864
	ds_read_b128 v[196:199], v170 offset:37888
	ds_read_b128 v[200:203], v170 offset:38912
	ds_read_b128 v[204:207], v170 offset:39936
	s_add_u32 s52, s48, 0x4000
	s_addc_u32 s53, s49, 0
	s_mov_b32 m0, s61
	s_nop 0
	global_load_lds_dwordx4 v166, s[52:53]
	s_add_u32 s52, s48, 0x6000
	s_addc_u32 s53, s49, 0
	s_mov_b32 m0, s62
	s_nop 0
	global_load_lds_dwordx4 v166, s[52:53]
	s_waitcnt vmcnt(8)
	s_waitcnt lgkmcnt(0)
	s_barrier
	s_setprio 1
	s_waitcnt lgkmcnt(7)
	s_waitcnt lgkmcnt(0)
	v_mfma_f32_16x16x32_bf16 v[112:115], v[128:131], v[176:179], v[112:115]
	v_mfma_f32_16x16x32_bf16 v[112:115], v[132:135], v[180:183], v[112:115]
	v_mfma_f32_16x16x32_bf16 v[96:99], v[128:131], v[184:187], v[96:99]
	v_mfma_f32_16x16x32_bf16 v[96:99], v[132:135], v[188:191], v[96:99]
	v_mfma_f32_16x16x32_bf16 v[80:83], v[128:131], v[192:195], v[80:83]
	v_mfma_f32_16x16x32_bf16 v[80:83], v[132:135], v[196:199], v[80:83]
	v_mfma_f32_16x16x32_bf16 v[60:63], v[128:131], v[200:203], v[60:63]
	v_mfma_f32_16x16x32_bf16 v[60:63], v[132:135], v[204:207], v[60:63]
	v_mfma_f32_16x16x32_bf16 v[72:75], v[136:139], v[200:203], v[72:75]
	v_mfma_f32_16x16x32_bf16 v[72:75], v[140:143], v[204:207], v[72:75]
	v_mfma_f32_16x16x32_bf16 v[88:91], v[136:139], v[192:195], v[88:91]
	v_mfma_f32_16x16x32_bf16 v[88:91], v[140:143], v[196:199], v[88:91]
	v_mfma_f32_16x16x32_bf16 v[104:107], v[136:139], v[184:187], v[104:107]
	v_mfma_f32_16x16x32_bf16 v[104:107], v[140:143], v[188:191], v[104:107]
	v_mfma_f32_16x16x32_bf16 v[120:123], v[136:139], v[176:179], v[120:123]
	v_mfma_f32_16x16x32_bf16 v[120:123], v[140:143], v[180:183], v[120:123]
	s_setprio 0
	s_setprio 1
	s_waitcnt lgkmcnt(0)
	v_mfma_f32_16x16x32_bf16 v[116:119], v[152:155], v[176:179], v[116:119]
	v_mfma_f32_16x16x32_bf16 v[116:119], v[156:159], v[180:183], v[116:119]
	v_mfma_f32_16x16x32_bf16 v[100:103], v[152:155], v[184:187], v[100:103]
	v_mfma_f32_16x16x32_bf16 v[100:103], v[156:159], v[188:191], v[100:103]
	v_mfma_f32_16x16x32_bf16 v[84:87], v[152:155], v[192:195], v[84:87]
	v_mfma_f32_16x16x32_bf16 v[84:87], v[156:159], v[196:199], v[84:87]
	v_mfma_f32_16x16x32_bf16 v[68:71], v[152:155], v[200:203], v[68:71]
	v_mfma_f32_16x16x32_bf16 v[68:71], v[156:159], v[204:207], v[68:71]
	v_mfma_f32_16x16x32_bf16 v[76:79], v[160:163], v[200:203], v[76:79]
	v_mfma_f32_16x16x32_bf16 v[76:79], v[172:175], v[204:207], v[76:79]
	v_mfma_f32_16x16x32_bf16 v[92:95], v[160:163], v[192:195], v[92:95]
	v_mfma_f32_16x16x32_bf16 v[92:95], v[172:175], v[196:199], v[92:95]
	v_mfma_f32_16x16x32_bf16 v[108:111], v[160:163], v[184:187], v[108:111]
	v_mfma_f32_16x16x32_bf16 v[108:111], v[172:175], v[188:191], v[108:111]
	v_mfma_f32_16x16x32_bf16 v[124:127], v[160:163], v[176:179], v[124:127]
	s_barrier
	v_mfma_f32_16x16x32_bf16 v[124:127], v[172:175], v[180:183], v[124:127]
	s_setprio 0
	s_add_u32 s52, s90, 0xa000
	ds_read_b128 v[176:179], v170 offset:49152
	ds_read_b128 v[180:183], v170 offset:50176
	ds_read_b128 v[184:187], v170 offset:51200
	ds_read_b128 v[188:191], v170 offset:52224
	ds_read_b128 v[192:195], v170 offset:53248
	ds_read_b128 v[196:199], v170 offset:54272
	ds_read_b128 v[200:203], v170 offset:55296
	ds_read_b128 v[204:207], v170 offset:56320
	s_mov_b32 m0, s66
	s_nop 0
	global_load_lds_dwordx4 v166, s[92:93]
	s_addc_u32 s53, s91, 0
	s_mov_b32 m0, s67
	s_nop 0
	global_load_lds_dwordx4 v166, s[52:53]
	s_add_u32 s52, s90, 0xc000
	s_addc_u32 s53, s91, 0
	s_mov_b32 m0, s70
	s_nop 0
	global_load_lds_dwordx4 v166, s[52:53]
	s_add_u32 s52, s90, 0xe000
	s_addc_u32 s53, s91, 0
	s_mov_b32 m0, s71
	s_nop 0
	global_load_lds_dwordx4 v166, s[52:53]
	s_add_u32 s48, s48, 0xa000
	s_mov_b32 m0, s68
	s_nop 0
	global_load_lds_dwordx4 v166, s[80:81]
	s_addc_u32 s49, s49, 0
	s_mov_b32 m0, s69
	s_nop 0
	global_load_lds_dwordx4 v166, s[48:49]
	s_waitcnt vmcnt(8)
	s_waitcnt lgkmcnt(0)
	s_barrier
	s_setprio 1
	s_waitcnt lgkmcnt(7)
	s_waitcnt lgkmcnt(0)
	v_mfma_f32_16x16x32_bf16 v[48:51], v[128:131], v[176:179], v[48:51]
	v_mfma_f32_16x16x32_bf16 v[48:51], v[132:135], v[180:183], v[48:51]
	v_mfma_f32_16x16x32_bf16 v[32:35], v[128:131], v[184:187], v[32:35]
	v_mfma_f32_16x16x32_bf16 v[32:35], v[132:135], v[188:191], v[32:35]
	v_mfma_f32_16x16x32_bf16 v[16:19], v[128:131], v[192:195], v[16:19]
	v_mfma_f32_16x16x32_bf16 v[16:19], v[132:135], v[196:199], v[16:19]
	v_mfma_f32_16x16x32_bf16 v[0:3], v[128:131], v[200:203], v[0:3]
	v_mfma_f32_16x16x32_bf16 v[0:3], v[132:135], v[204:207], v[0:3]
	v_mfma_f32_16x16x32_bf16 v[8:11], v[136:139], v[200:203], v[8:11]
	v_mfma_f32_16x16x32_bf16 v[8:11], v[140:143], v[204:207], v[8:11]
	v_mfma_f32_16x16x32_bf16 v[24:27], v[136:139], v[192:195], v[24:27]
	v_mfma_f32_16x16x32_bf16 v[24:27], v[140:143], v[196:199], v[24:27]
	v_mfma_f32_16x16x32_bf16 v[40:43], v[136:139], v[184:187], v[40:43]
	v_mfma_f32_16x16x32_bf16 v[40:43], v[140:143], v[188:191], v[40:43]
	v_mfma_f32_16x16x32_bf16 v[56:59], v[136:139], v[176:179], v[56:59]
	v_mfma_f32_16x16x32_bf16 v[56:59], v[140:143], v[180:183], v[56:59]
	s_setprio 0
	s_setprio 1
	s_waitcnt lgkmcnt(0)
	v_mfma_f32_16x16x32_bf16 v[52:55], v[152:155], v[176:179], v[52:55]
	v_mfma_f32_16x16x32_bf16 v[52:55], v[156:159], v[180:183], v[52:55]
	v_mfma_f32_16x16x32_bf16 v[36:39], v[152:155], v[184:187], v[36:39]
	v_mfma_f32_16x16x32_bf16 v[36:39], v[156:159], v[188:191], v[36:39]
	s_add_i32 s88, s88, 2
	v_mfma_f32_16x16x32_bf16 v[20:23], v[152:155], v[192:195], v[20:23]
	s_add_u32 s54, s54, 0x10000
	v_mfma_f32_16x16x32_bf16 v[20:23], v[156:159], v[196:199], v[20:23]
	s_addc_u32 s55, s55, 0
	v_mfma_f32_16x16x32_bf16 v[4:7], v[152:155], v[200:203], v[4:7]
	s_cmp_gt_u32 s88, 61
	v_mfma_f32_16x16x32_bf16 v[4:7], v[156:159], v[204:207], v[4:7]
	s_mov_b64 s[52:53], s[2:3]
	v_mfma_f32_16x16x32_bf16 v[12:15], v[160:163], v[200:203], v[12:15]
	v_mfma_f32_16x16x32_bf16 v[12:15], v[172:175], v[204:207], v[12:15]
	v_mfma_f32_16x16x32_bf16 v[28:31], v[160:163], v[192:195], v[28:31]
	v_mfma_f32_16x16x32_bf16 v[28:31], v[172:175], v[196:199], v[28:31]
	v_mfma_f32_16x16x32_bf16 v[44:47], v[160:163], v[184:187], v[44:47]
	v_mfma_f32_16x16x32_bf16 v[44:47], v[172:175], v[188:191], v[44:47]
	v_mfma_f32_16x16x32_bf16 v[64:67], v[160:163], v[176:179], v[64:67]
	s_barrier
	v_mfma_f32_16x16x32_bf16 v[64:67], v[172:175], v[180:183], v[64:67]
	s_setprio 0
	s_cbranch_scc0 .LBB0_170
	s_nop 7
	s_and_b64 vcc, exec, s[12:13]
	s_cbranch_vccz .LBB0_173
	s_barrier

.LBB0_326:
	ds_read_b128 v[60:63], v212
	ds_read_b128 v[68:71], v212 offset:1024
	ds_read_b128 v[88:91], v212 offset:2048
	ds_read_b128 v[92:95], v212 offset:3072
	ds_read_b128 v[112:115], v213
	ds_read_b128 v[116:119], v213 offset:1024
	ds_read_b128 v[138:141], v213 offset:2048
	ds_read_b128 v[152:155], v213 offset:3072
	s_cmpk_eq_i32 s80, 0xa8
	s_cselect_b32 s2, s4, s76
	s_cselect_b32 s3, s5, s77
	s_cselect_b32 s42, s38, s78
	s_cselect_b32 s43, s39, s79
	s_add_u32 s40, s2, 0x8000
	s_addc_u32 s41, s3, 0
	ds_read_b128 v[164:167], v214
	ds_read_b128 v[168:171], v214 offset:1024
	ds_read_b128 v[172:175], v214 offset:2048
	ds_read_b128 v[176:179], v214 offset:3072
	ds_read_b128 v[180:183], v214 offset:4096
	ds_read_b128 v[184:187], v214 offset:5120
	ds_read_b128 v[188:191], v214 offset:6144
	ds_read_b128 v[192:195], v214 offset:7168
	s_add_u32 s44, s76, 0xffffc000
	s_addc_u32 s45, s77, -1
	s_mov_b32 m0, s65
	s_nop 0
	global_load_lds_dwordx4 v210, s[44:45]
	s_add_u32 s44, s76, 0xffffe000
	s_addc_u32 s45, s77, -1
	s_mov_b32 m0, s68
	s_nop 0
	global_load_lds_dwordx4 v210, s[44:45]
	s_waitcnt vmcnt(8)
	s_waitcnt lgkmcnt(0)
	s_add_u32 s44, s42, 0x8000
	s_addc_u32 s45, s43, 0
	s_barrier
	s_setprio 1
	s_waitcnt lgkmcnt(7)
	s_waitcnt lgkmcnt(0)
	v_mfma_f32_16x16x32_bf16 v[160:163], v[60:63], v[164:167], v[160:163]
	v_mfma_f32_16x16x32_bf16 v[160:163], v[68:71], v[168:171], v[160:163]
	v_mfma_f32_16x16x32_bf16 v[132:135], v[60:63], v[172:175], v[132:135]
	v_mfma_f32_16x16x32_bf16 v[132:135], v[68:71], v[176:179], v[132:135]
	v_mfma_f32_16x16x32_bf16 v[108:111], v[60:63], v[180:183], v[108:111]
	v_mfma_f32_16x16x32_bf16 v[108:111], v[68:71], v[184:187], v[108:111]
	v_mfma_f32_16x16x32_bf16 v[84:87], v[60:63], v[188:191], v[84:87]
	v_mfma_f32_16x16x32_bf16 v[84:87], v[68:71], v[192:195], v[84:87]
	v_mfma_f32_16x16x32_bf16 v[80:83], v[88:91], v[188:191], v[80:83]
	v_mfma_f32_16x16x32_bf16 v[80:83], v[92:95], v[192:195], v[80:83]
	v_mfma_f32_16x16x32_bf16 v[104:107], v[88:91], v[180:183], v[104:107]
	v_mfma_f32_16x16x32_bf16 v[104:107], v[92:95], v[184:187], v[104:107]
	v_mfma_f32_16x16x32_bf16 v[128:131], v[88:91], v[172:175], v[128:131]
	v_mfma_f32_16x16x32_bf16 v[128:131], v[92:95], v[176:179], v[128:131]
	v_mfma_f32_16x16x32_bf16 v[156:159], v[88:91], v[164:167], v[156:159]
	v_mfma_f32_16x16x32_bf16 v[156:159], v[92:95], v[168:171], v[156:159]
	s_setprio 0
	s_setprio 1
	v_mfma_f32_16x16x32_bf16 v[148:151], v[112:115], v[164:167], v[148:151]
	v_mfma_f32_16x16x32_bf16 v[142:145], v[138:141], v[164:167], v[144:147]
	v_mfma_f32_16x16x32_bf16 v[124:127], v[112:115], v[172:175], v[124:127]
	v_mfma_f32_16x16x32_bf16 v[120:123], v[138:141], v[172:175], v[120:123]
	v_mfma_f32_16x16x32_bf16 v[100:103], v[112:115], v[180:183], v[100:103]
	v_mfma_f32_16x16x32_bf16 v[96:99], v[138:141], v[180:183], v[96:99]
	v_mfma_f32_16x16x32_bf16 v[76:79], v[112:115], v[188:191], v[76:79]
	v_mfma_f32_16x16x32_bf16 v[72:75], v[138:141], v[188:191], v[72:75]
	v_mfma_f32_16x16x32_bf16 v[148:151], v[116:119], v[168:171], v[148:151]
	v_mfma_f32_16x16x32_bf16 v[142:145], v[152:155], v[168:171], v[142:145]
	v_mfma_f32_16x16x32_bf16 v[124:127], v[116:119], v[176:179], v[124:127]
	v_mfma_f32_16x16x32_bf16 v[120:123], v[152:155], v[176:179], v[120:123]
	v_mfma_f32_16x16x32_bf16 v[100:103], v[116:119], v[184:187], v[100:103]
	v_mfma_f32_16x16x32_bf16 v[96:99], v[152:155], v[184:187], v[96:99]
	v_mfma_f32_16x16x32_bf16 v[76:79], v[116:119], v[192:195], v[76:79]
	v_mfma_f32_16x16x32_bf16 v[72:75], v[152:155], v[192:195], v[72:75]
	s_setprio 0
	s_barrier
	s_add_u32 s82, s42, 0x2000
	ds_read_b128 v[164:167], v214 offset:16384
	ds_read_b128 v[168:171], v214 offset:17408
	ds_read_b128 v[172:175], v214 offset:18432
	ds_read_b128 v[176:179], v214 offset:19456
	ds_read_b128 v[180:183], v214 offset:20480
	ds_read_b128 v[184:187], v214 offset:21504
	ds_read_b128 v[188:191], v214 offset:22528
	ds_read_b128 v[192:195], v214 offset:23552
	s_mov_b32 m0, s47
	s_nop 0
	global_load_lds_dwordx4 v210, s[42:43]
	s_addc_u32 s83, s43, 0
	s_mov_b32 m0, s48
	s_nop 0
	global_load_lds_dwordx4 v210, s[82:83]
	s_add_u32 s82, s42, 0x4000
	s_addc_u32 s83, s43, 0
	s_mov_b32 m0, s49
	s_nop 0
	global_load_lds_dwordx4 v210, s[82:83]
	s_add_u32 s82, s42, 0x6000
	s_addc_u32 s83, s43, 0
	s_mov_b32 m0, s52
	s_nop 0
	global_load_lds_dwordx4 v210, s[82:83]
	s_add_u32 s82, s2, 0x2000
	s_mov_b32 m0, s46
	s_nop 0
	global_load_lds_dwordx4 v210, s[2:3]
	s_addc_u32 s83, s3, 0
	s_mov_b32 m0, s53
	s_nop 0
	global_load_lds_dwordx4 v210, s[82:83]
	s_waitcnt vmcnt(8)
	s_waitcnt lgkmcnt(0)
	s_barrier
	s_setprio 1
	s_waitcnt lgkmcnt(7)
	s_waitcnt lgkmcnt(0)
	v_mfma_f32_16x16x32_bf16 v[64:67], v[60:63], v[164:167], v[64:67]
	v_mfma_f32_16x16x32_bf16 v[64:67], v[68:71], v[168:171], v[64:67]
	v_mfma_f32_16x16x32_bf16 v[44:47], v[60:63], v[172:175], v[44:47]
	v_mfma_f32_16x16x32_bf16 v[44:47], v[68:71], v[176:179], v[44:47]
	v_mfma_f32_16x16x32_bf16 v[28:31], v[60:63], v[180:183], v[28:31]
	v_mfma_f32_16x16x32_bf16 v[28:31], v[68:71], v[184:187], v[28:31]
	v_mfma_f32_16x16x32_bf16 v[12:15], v[60:63], v[188:191], v[12:15]
	v_mfma_f32_16x16x32_bf16 v[12:15], v[68:71], v[192:195], v[12:15]
	v_mfma_f32_16x16x32_bf16 v[8:11], v[88:91], v[188:191], v[8:11]
	v_mfma_f32_16x16x32_bf16 v[8:11], v[92:95], v[192:195], v[8:11]
	v_mfma_f32_16x16x32_bf16 v[24:27], v[88:91], v[180:183], v[24:27]
	v_mfma_f32_16x16x32_bf16 v[24:27], v[92:95], v[184:187], v[24:27]
	v_mfma_f32_16x16x32_bf16 v[40:43], v[88:91], v[172:175], v[40:43]
	v_mfma_f32_16x16x32_bf16 v[40:43], v[92:95], v[176:179], v[40:43]
	v_mfma_f32_16x16x32_bf16 v[56:59], v[88:91], v[164:167], v[56:59]
	v_mfma_f32_16x16x32_bf16 v[56:59], v[92:95], v[168:171], v[56:59]
	s_setprio 0
	s_setprio 1
	s_waitcnt lgkmcnt(0)
	v_mfma_f32_16x16x32_bf16 v[52:55], v[112:115], v[164:167], v[52:55]
	v_mfma_f32_16x16x32_bf16 v[52:55], v[116:119], v[168:171], v[52:55]
	v_mfma_f32_16x16x32_bf16 v[36:39], v[112:115], v[172:175], v[36:39]
	v_mfma_f32_16x16x32_bf16 v[36:39], v[116:119], v[176:179], v[36:39]
	v_mfma_f32_16x16x32_bf16 v[20:23], v[112:115], v[180:183], v[20:23]
	v_mfma_f32_16x16x32_bf16 v[20:23], v[116:119], v[184:187], v[20:23]
	v_mfma_f32_16x16x32_bf16 v[4:7], v[112:115], v[188:191], v[4:7]
	v_mfma_f32_16x16x32_bf16 v[4:7], v[116:119], v[192:195], v[4:7]
	v_mfma_f32_16x16x32_bf16 v[0:3], v[138:141], v[188:191], v[0:3]
	v_mfma_f32_16x16x32_bf16 v[0:3], v[152:155], v[192:195], v[0:3]
	v_mfma_f32_16x16x32_bf16 v[16:19], v[138:141], v[180:183], v[16:19]
	v_mfma_f32_16x16x32_bf16 v[16:19], v[152:155], v[184:187], v[16:19]
	v_mfma_f32_16x16x32_bf16 v[32:35], v[138:141], v[172:175], v[32:35]
	v_mfma_f32_16x16x32_bf16 v[32:35], v[152:155], v[176:179], v[32:35]
	v_mfma_f32_16x16x32_bf16 v[48:51], v[138:141], v[164:167], v[48:51]
	s_barrier
	v_mfma_f32_16x16x32_bf16 v[48:51], v[152:155], v[168:171], v[48:51]
	s_setprio 0
	ds_read_b128 v[60:63], v136
	ds_read_b128 v[68:71], v136 offset:1024
	ds_read_b128 v[88:91], v136 offset:2048
	ds_read_b128 v[92:95], v136 offset:3072
	ds_read_b128 v[112:115], v137
	ds_read_b128 v[116:119], v137 offset:1024
	ds_read_b128 v[138:141], v137 offset:2048
	ds_read_b128 v[152:155], v137 offset:3072
	ds_read_b128 v[164:167], v214 offset:32768
	ds_read_b128 v[168:171], v214 offset:33792
	ds_read_b128 v[172:175], v214 offset:34816
	ds_read_b128 v[176:179], v214 offset:35840
	ds_read_b128 v[180:183], v214 offset:36864
	ds_read_b128 v[184:187], v214 offset:37888
	ds_read_b128 v[188:191], v214 offset:38912
	ds_read_b128 v[192:195], v214 offset:39936
	s_add_u32 s82, s2, 0x4000
	s_addc_u32 s83, s3, 0
	s_mov_b32 m0, s54
	s_nop 0
	global_load_lds_dwordx4 v210, s[82:83]
	s_add_u32 s82, s2, 0x6000
	s_addc_u32 s83, s3, 0
	s_mov_b32 m0, s55
	s_nop 0
	global_load_lds_dwordx4 v210, s[82:83]
	s_waitcnt vmcnt(8)
	s_waitcnt lgkmcnt(0)
	s_barrier
	s_setprio 1
	s_waitcnt lgkmcnt(7)
	s_waitcnt lgkmcnt(0)
	v_mfma_f32_16x16x32_bf16 v[160:163], v[60:63], v[164:167], v[160:163]
	v_mfma_f32_16x16x32_bf16 v[160:163], v[68:71], v[168:171], v[160:163]
	v_mfma_f32_16x16x32_bf16 v[132:135], v[60:63], v[172:175], v[132:135]
	v_mfma_f32_16x16x32_bf16 v[132:135], v[68:71], v[176:179], v[132:135]
	v_mfma_f32_16x16x32_bf16 v[108:111], v[60:63], v[180:183], v[108:111]
	v_mfma_f32_16x16x32_bf16 v[108:111], v[68:71], v[184:187], v[108:111]
	v_mfma_f32_16x16x32_bf16 v[84:87], v[60:63], v[188:191], v[84:87]
	v_mfma_f32_16x16x32_bf16 v[84:87], v[68:71], v[192:195], v[84:87]
	v_mfma_f32_16x16x32_bf16 v[80:83], v[88:91], v[188:191], v[80:83]
	v_mfma_f32_16x16x32_bf16 v[80:83], v[92:95], v[192:195], v[80:83]
	v_mfma_f32_16x16x32_bf16 v[104:107], v[88:91], v[180:183], v[104:107]
	v_mfma_f32_16x16x32_bf16 v[104:107], v[92:95], v[184:187], v[104:107]
	v_mfma_f32_16x16x32_bf16 v[128:131], v[88:91], v[172:175], v[128:131]
	v_mfma_f32_16x16x32_bf16 v[128:131], v[92:95], v[176:179], v[128:131]
	v_mfma_f32_16x16x32_bf16 v[156:159], v[88:91], v[164:167], v[156:159]
	v_mfma_f32_16x16x32_bf16 v[156:159], v[92:95], v[168:171], v[156:159]
	s_setprio 0
	s_setprio 1
	v_mfma_f32_16x16x32_bf16 v[146:149], v[112:115], v[164:167], v[148:151]
	v_mfma_f32_16x16x32_bf16 v[142:145], v[138:141], v[164:167], v[142:145]
	v_mfma_f32_16x16x32_bf16 v[124:127], v[112:115], v[172:175], v[124:127]
	v_mfma_f32_16x16x32_bf16 v[120:123], v[138:141], v[172:175], v[120:123]
	v_mfma_f32_16x16x32_bf16 v[100:103], v[112:115], v[180:183], v[100:103]
	v_mfma_f32_16x16x32_bf16 v[96:99], v[138:141], v[180:183], v[96:99]
	v_mfma_f32_16x16x32_bf16 v[76:79], v[112:115], v[188:191], v[76:79]
	v_mfma_f32_16x16x32_bf16 v[72:75], v[138:141], v[188:191], v[72:75]
	v_mfma_f32_16x16x32_bf16 v[148:151], v[116:119], v[168:171], v[146:149]
	v_mfma_f32_16x16x32_bf16 v[144:147], v[152:155], v[168:171], v[142:145]
	v_mfma_f32_16x16x32_bf16 v[124:127], v[116:119], v[176:179], v[124:127]
	v_mfma_f32_16x16x32_bf16 v[120:123], v[152:155], v[176:179], v[120:123]
	v_mfma_f32_16x16x32_bf16 v[100:103], v[116:119], v[184:187], v[100:103]
	v_mfma_f32_16x16x32_bf16 v[96:99], v[152:155], v[184:187], v[96:99]
	v_mfma_f32_16x16x32_bf16 v[76:79], v[116:119], v[192:195], v[76:79]
	v_mfma_f32_16x16x32_bf16 v[72:75], v[152:155], v[192:195], v[72:75]
	s_setprio 0
	s_barrier
	ds_read_b128 v[164:167], v214 offset:49152
	ds_read_b128 v[168:171], v214 offset:50176
	ds_read_b128 v[172:175], v214 offset:51200
	ds_read_b128 v[176:179], v214 offset:52224
	ds_read_b128 v[180:183], v214 offset:53248
	ds_read_b128 v[184:187], v214 offset:54272
	ds_read_b128 v[188:191], v214 offset:55296
	ds_read_b128 v[192:195], v214 offset:56320
	s_mov_b32 m0, s59
	s_nop 0
	global_load_lds_dwordx4 v210, s[44:45]
	s_add_u32 s44, s42, 0xa000
	s_addc_u32 s45, s43, 0
	s_mov_b32 m0, s60
	s_nop 0
	global_load_lds_dwordx4 v210, s[44:45]
	s_add_u32 s44, s42, 0xc000
	s_addc_u32 s45, s43, 0
	s_mov_b32 m0, s63
	s_nop 0
	global_load_lds_dwordx4 v210, s[44:45]
	s_add_u32 s42, s42, 0xe000
	s_addc_u32 s43, s43, 0
	s_mov_b32 m0, s64
	s_nop 0
	global_load_lds_dwordx4 v210, s[42:43]
	s_add_u32 s2, s2, 0xa000
	s_mov_b32 m0, s61
	s_nop 0
	global_load_lds_dwordx4 v210, s[40:41]
	s_addc_u32 s3, s3, 0
	s_mov_b32 m0, s62
	s_nop 0
	global_load_lds_dwordx4 v210, s[2:3]
	s_waitcnt vmcnt(8)
	s_waitcnt lgkmcnt(0)
	s_barrier
	s_setprio 1
	s_waitcnt lgkmcnt(7)
	s_waitcnt lgkmcnt(0)
	v_mfma_f32_16x16x32_bf16 v[64:67], v[60:63], v[164:167], v[64:67]
	v_mfma_f32_16x16x32_bf16 v[64:67], v[68:71], v[168:171], v[64:67]
	v_mfma_f32_16x16x32_bf16 v[44:47], v[60:63], v[172:175], v[44:47]
	v_mfma_f32_16x16x32_bf16 v[44:47], v[68:71], v[176:179], v[44:47]
	v_mfma_f32_16x16x32_bf16 v[28:31], v[60:63], v[180:183], v[28:31]
	v_mfma_f32_16x16x32_bf16 v[28:31], v[68:71], v[184:187], v[28:31]
	v_mfma_f32_16x16x32_bf16 v[12:15], v[60:63], v[188:191], v[12:15]
	v_mfma_f32_16x16x32_bf16 v[12:15], v[68:71], v[192:195], v[12:15]
	v_mfma_f32_16x16x32_bf16 v[8:11], v[88:91], v[188:191], v[8:11]
	v_mfma_f32_16x16x32_bf16 v[8:11], v[92:95], v[192:195], v[8:11]
	v_mfma_f32_16x16x32_bf16 v[24:27], v[88:91], v[180:183], v[24:27]
	v_mfma_f32_16x16x32_bf16 v[24:27], v[92:95], v[184:187], v[24:27]
	v_mfma_f32_16x16x32_bf16 v[40:43], v[88:91], v[172:175], v[40:43]
	v_mfma_f32_16x16x32_bf16 v[40:43], v[92:95], v[176:179], v[40:43]
	v_mfma_f32_16x16x32_bf16 v[56:59], v[88:91], v[164:167], v[56:59]
	v_mfma_f32_16x16x32_bf16 v[56:59], v[92:95], v[168:171], v[56:59]
	s_setprio 0
	s_setprio 1
	s_waitcnt lgkmcnt(0)
	v_mfma_f32_16x16x32_bf16 v[52:55], v[112:115], v[164:167], v[52:55]
	v_mfma_f32_16x16x32_bf16 v[52:55], v[116:119], v[168:171], v[52:55]
	v_mfma_f32_16x16x32_bf16 v[36:39], v[112:115], v[172:175], v[36:39]
	v_mfma_f32_16x16x32_bf16 v[36:39], v[116:119], v[176:179], v[36:39]
	s_add_i32 s80, s80, 2
	v_mfma_f32_16x16x32_bf16 v[20:23], v[112:115], v[180:183], v[20:23]
	s_add_u32 s76, s76, 0x10000
	v_mfma_f32_16x16x32_bf16 v[20:23], v[116:119], v[184:187], v[20:23]
	s_addc_u32 s77, s77, 0
	v_mfma_f32_16x16x32_bf16 v[4:7], v[112:115], v[188:191], v[4:7]
	s_add_u32 s78, s78, 0x10000
	v_mfma_f32_16x16x32_bf16 v[4:7], v[116:119], v[192:195], v[4:7]
	s_addc_u32 s79, s79, 0
	v_mfma_f32_16x16x32_bf16 v[0:3], v[138:141], v[188:191], v[0:3]
	s_cmpk_gt_u32 s80, 0xa9
	v_mfma_f32_16x16x32_bf16 v[0:3], v[152:155], v[192:195], v[0:3]
	v_mfma_f32_16x16x32_bf16 v[16:19], v[138:141], v[180:183], v[16:19]
	v_mfma_f32_16x16x32_bf16 v[16:19], v[152:155], v[184:187], v[16:19]
	v_mfma_f32_16x16x32_bf16 v[32:35], v[138:141], v[172:175], v[32:35]
	v_mfma_f32_16x16x32_bf16 v[32:35], v[152:155], v[176:179], v[32:35]
	v_mfma_f32_16x16x32_bf16 v[48:51], v[138:141], v[164:167], v[48:51]
	s_barrier
	v_mfma_f32_16x16x32_bf16 v[48:51], v[152:155], v[168:171], v[48:51]
	s_setprio 0
	s_cbranch_scc0 .LBB0_326
	s_nop 7
	s_and_b64 vcc, exec, s[12:13]
	s_cbranch_vccz .LBB0_329
	s_barrier

.LBB0_425:
	ds_read_b128 v[128:131], v162
	ds_read_b128 v[132:135], v162 offset:1024
	ds_read_b128 v[136:139], v162 offset:2048
	ds_read_b128 v[140:143], v162 offset:3072
	ds_read_b128 v[152:155], v163
	ds_read_b128 v[156:159], v163 offset:1024
	ds_read_b128 v[168:171], v163 offset:2048
	ds_read_b128 v[172:175], v163 offset:3072
	s_add_u32 s48, s52, 0x10000
	s_addc_u32 s49, s53, 0
	s_cmp_eq_u32 s79, 60
	s_cselect_b32 s80, s10, s48
	s_cselect_b32 s81, s5, s49
	s_cselect_b32 s96, s47, s77
	s_cselect_b32 s97, s45, s78
	s_add_u32 s2, s80, 0x8000
	s_addc_u32 s3, s81, 0
	ds_read_b128 v[176:179], v164
	ds_read_b128 v[180:183], v164 offset:1024
	ds_read_b128 v[184:187], v164 offset:2048
	ds_read_b128 v[188:191], v164 offset:3072
	ds_read_b128 v[192:195], v164 offset:4096
	ds_read_b128 v[196:199], v164 offset:5120
	ds_read_b128 v[200:203], v164 offset:6144
	ds_read_b128 v[204:207], v164 offset:7168
	s_add_u32 s82, s52, 0xc000
	s_addc_u32 s83, s53, 0
	s_mov_b32 m0, s70
	s_nop 0
	global_load_lds_dwordx4 v160, s[82:83]
	s_add_u32 s52, s52, 0xe000
	s_addc_u32 s53, s53, 0
	s_mov_b32 m0, s71
	s_nop 0
	global_load_lds_dwordx4 v160, s[52:53]
	s_waitcnt vmcnt(8)
	s_waitcnt lgkmcnt(0)
	s_add_u32 s52, s96, 0x8000
	s_addc_u32 s53, s97, 0
	s_barrier
	s_setprio 1
	s_waitcnt lgkmcnt(7)
	s_waitcnt lgkmcnt(0)
	v_mfma_f32_16x16x32_bf16 v[124:127], v[128:131], v[176:179], v[124:127]
	v_mfma_f32_16x16x32_bf16 v[124:127], v[132:135], v[180:183], v[124:127]
	v_mfma_f32_16x16x32_bf16 v[108:111], v[128:131], v[184:187], v[108:111]
	v_mfma_f32_16x16x32_bf16 v[108:111], v[132:135], v[188:191], v[108:111]
	v_mfma_f32_16x16x32_bf16 v[92:95], v[128:131], v[192:195], v[92:95]
	v_mfma_f32_16x16x32_bf16 v[92:95], v[132:135], v[196:199], v[92:95]
	v_mfma_f32_16x16x32_bf16 v[76:79], v[128:131], v[200:203], v[76:79]
	v_mfma_f32_16x16x32_bf16 v[76:79], v[132:135], v[204:207], v[76:79]
	v_mfma_f32_16x16x32_bf16 v[72:75], v[136:139], v[200:203], v[72:75]
	v_mfma_f32_16x16x32_bf16 v[72:75], v[140:143], v[204:207], v[72:75]
	v_mfma_f32_16x16x32_bf16 v[88:91], v[136:139], v[192:195], v[88:91]
	v_mfma_f32_16x16x32_bf16 v[88:91], v[140:143], v[196:199], v[88:91]
	v_mfma_f32_16x16x32_bf16 v[104:107], v[136:139], v[184:187], v[104:107]
	v_mfma_f32_16x16x32_bf16 v[104:107], v[140:143], v[188:191], v[104:107]
	v_mfma_f32_16x16x32_bf16 v[120:123], v[136:139], v[176:179], v[120:123]
	v_mfma_f32_16x16x32_bf16 v[120:123], v[140:143], v[180:183], v[120:123]
	s_setprio 0
	s_setprio 1
	s_waitcnt lgkmcnt(0)
	v_mfma_f32_16x16x32_bf16 v[116:119], v[152:155], v[176:179], v[116:119]
	v_mfma_f32_16x16x32_bf16 v[116:119], v[156:159], v[180:183], v[116:119]
	v_mfma_f32_16x16x32_bf16 v[100:103], v[152:155], v[184:187], v[100:103]
	v_mfma_f32_16x16x32_bf16 v[100:103], v[156:159], v[188:191], v[100:103]
	v_mfma_f32_16x16x32_bf16 v[84:87], v[152:155], v[192:195], v[84:87]
	v_mfma_f32_16x16x32_bf16 v[84:87], v[156:159], v[196:199], v[84:87]
	v_mfma_f32_16x16x32_bf16 v[68:71], v[152:155], v[200:203], v[68:71]
	v_mfma_f32_16x16x32_bf16 v[68:71], v[156:159], v[204:207], v[68:71]
	v_mfma_f32_16x16x32_bf16 v[64:67], v[168:171], v[200:203], v[64:67]
	v_mfma_f32_16x16x32_bf16 v[64:67], v[172:175], v[204:207], v[64:67]
	v_mfma_f32_16x16x32_bf16 v[80:83], v[168:171], v[192:195], v[80:83]
	v_mfma_f32_16x16x32_bf16 v[80:83], v[172:175], v[196:199], v[80:83]
	v_mfma_f32_16x16x32_bf16 v[96:99], v[168:171], v[184:187], v[96:99]
	v_mfma_f32_16x16x32_bf16 v[96:99], v[172:175], v[188:191], v[96:99]
	v_mfma_f32_16x16x32_bf16 v[112:115], v[168:171], v[176:179], v[112:115]
	s_barrier
	v_mfma_f32_16x16x32_bf16 v[112:115], v[172:175], v[180:183], v[112:115]
	s_setprio 0
	s_add_u32 s82, s96, 0x2000
	ds_read_b128 v[176:179], v164 offset:16384
	ds_read_b128 v[180:183], v164 offset:17408
	ds_read_b128 v[184:187], v164 offset:18432
	ds_read_b128 v[188:191], v164 offset:19456
	ds_read_b128 v[192:195], v164 offset:20480
	ds_read_b128 v[196:199], v164 offset:21504
	ds_read_b128 v[200:203], v164 offset:22528
	ds_read_b128 v[204:207], v164 offset:23552
	s_mov_b32 m0, s55
	s_nop 0
	global_load_lds_dwordx4 v160, s[96:97]
	s_addc_u32 s83, s97, 0
	s_mov_b32 m0, s56
	s_nop 0
	global_load_lds_dwordx4 v160, s[82:83]
	s_add_u32 s82, s96, 0x4000
	s_addc_u32 s83, s97, 0
	s_mov_b32 m0, s57
	s_nop 0
	global_load_lds_dwordx4 v160, s[82:83]
	s_add_u32 s82, s96, 0x6000
	s_addc_u32 s83, s97, 0
	s_mov_b32 m0, s58
	s_nop 0
	global_load_lds_dwordx4 v160, s[82:83]
	s_add_u32 s82, s80, 0x2000
	s_mov_b32 m0, s54
	s_nop 0
	global_load_lds_dwordx4 v160, s[80:81]
	s_addc_u32 s83, s81, 0
	s_mov_b32 m0, s59
	s_nop 0
	global_load_lds_dwordx4 v160, s[82:83]
	s_waitcnt vmcnt(8)
	s_waitcnt lgkmcnt(0)
	s_barrier
	s_setprio 1
	s_waitcnt lgkmcnt(7)
	s_waitcnt lgkmcnt(0)
	v_mfma_f32_16x16x32_bf16 v[60:63], v[128:131], v[176:179], v[60:63]
	v_mfma_f32_16x16x32_bf16 v[60:63], v[132:135], v[180:183], v[60:63]
	v_mfma_f32_16x16x32_bf16 v[44:47], v[128:131], v[184:187], v[44:47]
	v_mfma_f32_16x16x32_bf16 v[44:47], v[132:135], v[188:191], v[44:47]
	v_mfma_f32_16x16x32_bf16 v[28:31], v[128:131], v[192:195], v[28:31]
	v_mfma_f32_16x16x32_bf16 v[28:31], v[132:135], v[196:199], v[28:31]
	v_mfma_f32_16x16x32_bf16 v[12:15], v[128:131], v[200:203], v[12:15]
	v_mfma_f32_16x16x32_bf16 v[12:15], v[132:135], v[204:207], v[12:15]
	v_mfma_f32_16x16x32_bf16 v[8:11], v[136:139], v[200:203], v[8:11]
	v_mfma_f32_16x16x32_bf16 v[8:11], v[140:143], v[204:207], v[8:11]
	v_mfma_f32_16x16x32_bf16 v[24:27], v[136:139], v[192:195], v[24:27]
	v_mfma_f32_16x16x32_bf16 v[24:27], v[140:143], v[196:199], v[24:27]
	v_mfma_f32_16x16x32_bf16 v[40:43], v[136:139], v[184:187], v[40:43]
	v_mfma_f32_16x16x32_bf16 v[40:43], v[140:143], v[188:191], v[40:43]
	v_mfma_f32_16x16x32_bf16 v[56:59], v[136:139], v[176:179], v[56:59]
	v_mfma_f32_16x16x32_bf16 v[56:59], v[140:143], v[180:183], v[56:59]
	s_setprio 0
	s_setprio 1
	s_waitcnt lgkmcnt(0)
	v_mfma_f32_16x16x32_bf16 v[52:55], v[152:155], v[176:179], v[52:55]
	v_mfma_f32_16x16x32_bf16 v[52:55], v[156:159], v[180:183], v[52:55]
	v_mfma_f32_16x16x32_bf16 v[36:39], v[152:155], v[184:187], v[36:39]
	v_mfma_f32_16x16x32_bf16 v[36:39], v[156:159], v[188:191], v[36:39]
	v_mfma_f32_16x16x32_bf16 v[20:23], v[152:155], v[192:195], v[20:23]
	v_mfma_f32_16x16x32_bf16 v[20:23], v[156:159], v[196:199], v[20:23]
	v_mfma_f32_16x16x32_bf16 v[4:7], v[152:155], v[200:203], v[4:7]
	v_mfma_f32_16x16x32_bf16 v[4:7], v[156:159], v[204:207], v[4:7]
	v_mfma_f32_16x16x32_bf16 v[0:3], v[168:171], v[200:203], v[0:3]
	v_mfma_f32_16x16x32_bf16 v[0:3], v[172:175], v[204:207], v[0:3]
	v_mfma_f32_16x16x32_bf16 v[16:19], v[168:171], v[192:195], v[16:19]
	v_mfma_f32_16x16x32_bf16 v[16:19], v[172:175], v[196:199], v[16:19]
	v_mfma_f32_16x16x32_bf16 v[32:35], v[168:171], v[184:187], v[32:35]
	v_mfma_f32_16x16x32_bf16 v[32:35], v[172:175], v[188:191], v[32:35]
	v_mfma_f32_16x16x32_bf16 v[48:51], v[168:171], v[176:179], v[48:51]
	s_barrier
	v_mfma_f32_16x16x32_bf16 v[48:51], v[172:175], v[180:183], v[48:51]
	s_setprio 0
	ds_read_b128 v[128:131], v148
	ds_read_b128 v[132:135], v148 offset:1024
	ds_read_b128 v[136:139], v148 offset:2048
	ds_read_b128 v[140:143], v148 offset:3072
	ds_read_b128 v[152:155], v150
	ds_read_b128 v[156:159], v150 offset:1024
	ds_read_b128 v[168:171], v150 offset:2048
	ds_read_b128 v[172:175], v150 offset:3072
	ds_read_b128 v[176:179], v164 offset:32768
	ds_read_b128 v[180:183], v164 offset:33792
	ds_read_b128 v[184:187], v164 offset:34816
	ds_read_b128 v[188:191], v164 offset:35840
	ds_read_b128 v[192:195], v164 offset:36864
	ds_read_b128 v[196:199], v164 offset:37888
	ds_read_b128 v[200:203], v164 offset:38912
	ds_read_b128 v[204:207], v164 offset:39936
	s_add_u32 s82, s80, 0x4000
	s_addc_u32 s83, s81, 0
	s_mov_b32 m0, s60
	s_nop 0
	global_load_lds_dwordx4 v160, s[82:83]
	s_add_u32 s82, s80, 0x6000
	s_addc_u32 s83, s81, 0
	s_mov_b32 m0, s61
	s_nop 0
	global_load_lds_dwordx4 v160, s[82:83]
	s_waitcnt vmcnt(8)
	s_waitcnt lgkmcnt(0)
	s_barrier
	s_setprio 1
	s_waitcnt lgkmcnt(7)
	s_waitcnt lgkmcnt(0)
	v_mfma_f32_16x16x32_bf16 v[124:127], v[128:131], v[176:179], v[124:127]
	v_mfma_f32_16x16x32_bf16 v[124:127], v[132:135], v[180:183], v[124:127]
	v_mfma_f32_16x16x32_bf16 v[108:111], v[128:131], v[184:187], v[108:111]
	v_mfma_f32_16x16x32_bf16 v[108:111], v[132:135], v[188:191], v[108:111]
	v_mfma_f32_16x16x32_bf16 v[92:95], v[128:131], v[192:195], v[92:95]
	v_mfma_f32_16x16x32_bf16 v[92:95], v[132:135], v[196:199], v[92:95]
	v_mfma_f32_16x16x32_bf16 v[76:79], v[128:131], v[200:203], v[76:79]
	v_mfma_f32_16x16x32_bf16 v[76:79], v[132:135], v[204:207], v[76:79]
	v_mfma_f32_16x16x32_bf16 v[72:75], v[136:139], v[200:203], v[72:75]
	v_mfma_f32_16x16x32_bf16 v[72:75], v[140:143], v[204:207], v[72:75]
	v_mfma_f32_16x16x32_bf16 v[88:91], v[136:139], v[192:195], v[88:91]
	v_mfma_f32_16x16x32_bf16 v[88:91], v[140:143], v[196:199], v[88:91]
	v_mfma_f32_16x16x32_bf16 v[104:107], v[136:139], v[184:187], v[104:107]
	v_mfma_f32_16x16x32_bf16 v[104:107], v[140:143], v[188:191], v[104:107]
	v_mfma_f32_16x16x32_bf16 v[120:123], v[136:139], v[176:179], v[120:123]
	v_mfma_f32_16x16x32_bf16 v[120:123], v[140:143], v[180:183], v[120:123]
	s_setprio 0
	s_setprio 1
	s_waitcnt lgkmcnt(0)
	v_mfma_f32_16x16x32_bf16 v[116:119], v[152:155], v[176:179], v[116:119]
	v_mfma_f32_16x16x32_bf16 v[116:119], v[156:159], v[180:183], v[116:119]
	v_mfma_f32_16x16x32_bf16 v[100:103], v[152:155], v[184:187], v[100:103]
	v_mfma_f32_16x16x32_bf16 v[100:103], v[156:159], v[188:191], v[100:103]
	v_mfma_f32_16x16x32_bf16 v[84:87], v[152:155], v[192:195], v[84:87]
	v_mfma_f32_16x16x32_bf16 v[84:87], v[156:159], v[196:199], v[84:87]
	v_mfma_f32_16x16x32_bf16 v[68:71], v[152:155], v[200:203], v[68:71]
	v_mfma_f32_16x16x32_bf16 v[68:71], v[156:159], v[204:207], v[68:71]
	v_mfma_f32_16x16x32_bf16 v[64:67], v[168:171], v[200:203], v[64:67]
	v_mfma_f32_16x16x32_bf16 v[64:67], v[172:175], v[204:207], v[64:67]
	v_mfma_f32_16x16x32_bf16 v[80:83], v[168:171], v[192:195], v[80:83]
	v_mfma_f32_16x16x32_bf16 v[80:83], v[172:175], v[196:199], v[80:83]
	v_mfma_f32_16x16x32_bf16 v[96:99], v[168:171], v[184:187], v[96:99]
	v_mfma_f32_16x16x32_bf16 v[96:99], v[172:175], v[188:191], v[96:99]
	v_mfma_f32_16x16x32_bf16 v[112:115], v[168:171], v[176:179], v[112:115]
	s_barrier
	v_mfma_f32_16x16x32_bf16 v[112:115], v[172:175], v[180:183], v[112:115]
	s_setprio 0
	ds_read_b128 v[176:179], v164 offset:49152
	ds_read_b128 v[180:183], v164 offset:50176
	ds_read_b128 v[184:187], v164 offset:51200
	ds_read_b128 v[188:191], v164 offset:52224
	ds_read_b128 v[192:195], v164 offset:53248
	ds_read_b128 v[196:199], v164 offset:54272
	ds_read_b128 v[200:203], v164 offset:55296
	ds_read_b128 v[204:207], v164 offset:56320
	s_mov_b32 m0, s64
	s_nop 0
	global_load_lds_dwordx4 v160, s[52:53]
	s_add_u32 s52, s96, 0xa000
	s_addc_u32 s53, s97, 0
	s_mov_b32 m0, s65
	s_nop 0
	global_load_lds_dwordx4 v160, s[52:53]
	s_add_u32 s52, s96, 0xc000
	s_addc_u32 s53, s97, 0
	s_mov_b32 m0, s68
	s_nop 0
	global_load_lds_dwordx4 v160, s[52:53]
	s_add_u32 s52, s96, 0xe000
	s_addc_u32 s53, s97, 0
	s_mov_b32 m0, s69
	s_nop 0
	global_load_lds_dwordx4 v160, s[52:53]
	s_nop 0
	s_mov_b32 m0, s66
	s_nop 0
	global_load_lds_dwordx4 v160, s[2:3]
	s_add_u32 s2, s80, 0xa000
	s_addc_u32 s3, s81, 0
	s_mov_b32 m0, s67
	s_nop 0
	global_load_lds_dwordx4 v160, s[2:3]
	s_waitcnt vmcnt(8)
	s_waitcnt lgkmcnt(0)
	s_barrier
	s_setprio 1
	s_waitcnt lgkmcnt(7)
	s_waitcnt lgkmcnt(0)
	v_mfma_f32_16x16x32_bf16 v[60:63], v[128:131], v[176:179], v[60:63]
	v_mfma_f32_16x16x32_bf16 v[60:63], v[132:135], v[180:183], v[60:63]
	v_mfma_f32_16x16x32_bf16 v[44:47], v[128:131], v[184:187], v[44:47]
	v_mfma_f32_16x16x32_bf16 v[44:47], v[132:135], v[188:191], v[44:47]
	v_mfma_f32_16x16x32_bf16 v[28:31], v[128:131], v[192:195], v[28:31]
	v_mfma_f32_16x16x32_bf16 v[28:31], v[132:135], v[196:199], v[28:31]
	v_mfma_f32_16x16x32_bf16 v[12:15], v[128:131], v[200:203], v[12:15]
	v_mfma_f32_16x16x32_bf16 v[12:15], v[132:135], v[204:207], v[12:15]
	v_mfma_f32_16x16x32_bf16 v[8:11], v[136:139], v[200:203], v[8:11]
	v_mfma_f32_16x16x32_bf16 v[8:11], v[140:143], v[204:207], v[8:11]
	v_mfma_f32_16x16x32_bf16 v[24:27], v[136:139], v[192:195], v[24:27]
	v_mfma_f32_16x16x32_bf16 v[24:27], v[140:143], v[196:199], v[24:27]
	v_mfma_f32_16x16x32_bf16 v[40:43], v[136:139], v[184:187], v[40:43]
	v_mfma_f32_16x16x32_bf16 v[40:43], v[140:143], v[188:191], v[40:43]
	v_mfma_f32_16x16x32_bf16 v[56:59], v[136:139], v[176:179], v[56:59]
	v_mfma_f32_16x16x32_bf16 v[56:59], v[140:143], v[180:183], v[56:59]
	s_setprio 0
	s_setprio 1
	s_waitcnt lgkmcnt(0)
	v_mfma_f32_16x16x32_bf16 v[52:55], v[152:155], v[176:179], v[52:55]
	v_mfma_f32_16x16x32_bf16 v[52:55], v[156:159], v[180:183], v[52:55]
	v_mfma_f32_16x16x32_bf16 v[36:39], v[152:155], v[184:187], v[36:39]
	v_mfma_f32_16x16x32_bf16 v[36:39], v[156:159], v[188:191], v[36:39]
	s_add_i32 s79, s79, 2
	v_mfma_f32_16x16x32_bf16 v[20:23], v[152:155], v[192:195], v[20:23]
	s_add_u32 s77, s77, 0x10000
	v_mfma_f32_16x16x32_bf16 v[20:23], v[156:159], v[196:199], v[20:23]
	s_addc_u32 s78, s78, 0
	v_mfma_f32_16x16x32_bf16 v[4:7], v[152:155], v[200:203], v[4:7]
	s_cmp_gt_u32 s79, 61
	v_mfma_f32_16x16x32_bf16 v[4:7], v[156:159], v[204:207], v[4:7]
	s_mov_b64 s[52:53], s[48:49]
	v_mfma_f32_16x16x32_bf16 v[0:3], v[168:171], v[200:203], v[0:3]
	v_mfma_f32_16x16x32_bf16 v[0:3], v[172:175], v[204:207], v[0:3]
	v_mfma_f32_16x16x32_bf16 v[16:19], v[168:171], v[192:195], v[16:19]
	v_mfma_f32_16x16x32_bf16 v[16:19], v[172:175], v[196:199], v[16:19]
	v_mfma_f32_16x16x32_bf16 v[32:35], v[168:171], v[184:187], v[32:35]
	v_mfma_f32_16x16x32_bf16 v[32:35], v[172:175], v[188:191], v[32:35]
	v_mfma_f32_16x16x32_bf16 v[48:51], v[168:171], v[176:179], v[48:51]
	s_barrier
	v_mfma_f32_16x16x32_bf16 v[48:51], v[172:175], v[180:183], v[48:51]
	s_setprio 0
	s_cbranch_scc0 .LBB0_425
	s_nop 7
	s_and_b64 vcc, exec, s[14:15]
	s_cbranch_vccz .LBB0_428
	s_barrier

.LBB0_1406:
	ds_read_b128 v[72:75], v212
	ds_read_b128 v[84:87], v212 offset:1024
	ds_read_b128 v[96:99], v212 offset:2048
	ds_read_b128 v[108:111], v212 offset:3072
	ds_read_b128 v[112:115], v213
	ds_read_b128 v[136:139], v213 offset:1024
	ds_read_b128 v[148:151], v213 offset:2048
	ds_read_b128 v[160:163], v213 offset:3072
	s_cmp_eq_u32 s90, 60
	s_cselect_b32 s2, s82, s54
	s_cselect_b32 s3, s41, s55
	s_cselect_b32 s58, s83, s88
	s_cselect_b32 s59, s39, s89
	s_add_u32 s56, s2, 0x8000
	s_addc_u32 s57, s3, 0
	ds_read_b128 v[164:167], v214
	ds_read_b128 v[168:171], v214 offset:1024
	ds_read_b128 v[172:175], v214 offset:2048
	ds_read_b128 v[176:179], v214 offset:3072
	ds_read_b128 v[180:183], v214 offset:4096
	ds_read_b128 v[184:187], v214 offset:5120
	ds_read_b128 v[188:191], v214 offset:6144
	ds_read_b128 v[192:195], v214 offset:7168
	s_add_u32 s52, s54, 0xffffc000
	s_addc_u32 s53, s55, -1
	s_mov_b32 m0, s75
	s_nop 0
	global_load_lds_dwordx4 v210, s[52:53]
	s_add_u32 s52, s54, 0xffffe000
	s_addc_u32 s53, s55, -1
	s_mov_b32 m0, s78
	s_nop 0
	global_load_lds_dwordx4 v210, s[52:53]
	s_waitcnt vmcnt(8)
	s_waitcnt lgkmcnt(0)
	s_add_u32 s52, s58, 0x8000
	s_addc_u32 s53, s59, 0
	s_barrier
	s_setprio 1
	s_waitcnt lgkmcnt(7)
	v_mfma_f32_16x16x32_bf16 v[156:159], v[72:75], v[164:167], v[156:159]
	v_mfma_f32_16x16x32_bf16 v[152:155], v[96:99], v[164:167], v[152:155]
	s_waitcnt lgkmcnt(5)
	v_mfma_f32_16x16x32_bf16 v[132:135], v[72:75], v[172:175], v[132:135]
	v_mfma_f32_16x16x32_bf16 v[126:129], v[96:99], v[172:175], v[128:131]
	s_waitcnt lgkmcnt(3)
	v_mfma_f32_16x16x32_bf16 v[104:107], v[72:75], v[180:183], v[104:107]
	v_mfma_f32_16x16x32_bf16 v[100:103], v[96:99], v[180:183], v[100:103]
	s_waitcnt lgkmcnt(1)
	v_mfma_f32_16x16x32_bf16 v[80:83], v[72:75], v[188:191], v[80:83]
	v_mfma_f32_16x16x32_bf16 v[76:79], v[96:99], v[188:191], v[76:79]
	v_mfma_f32_16x16x32_bf16 v[156:159], v[84:87], v[168:171], v[156:159]
	v_mfma_f32_16x16x32_bf16 v[152:155], v[108:111], v[168:171], v[152:155]
	v_mfma_f32_16x16x32_bf16 v[132:135], v[84:87], v[176:179], v[132:135]
	v_mfma_f32_16x16x32_bf16 v[126:129], v[108:111], v[176:179], v[126:129]
	v_mfma_f32_16x16x32_bf16 v[104:107], v[84:87], v[184:187], v[104:107]
	v_mfma_f32_16x16x32_bf16 v[100:103], v[108:111], v[184:187], v[100:103]
	s_waitcnt lgkmcnt(0)
	v_mfma_f32_16x16x32_bf16 v[80:83], v[84:87], v[192:195], v[80:83]
	v_mfma_f32_16x16x32_bf16 v[76:79], v[108:111], v[192:195], v[76:79]
	s_setprio 0
	s_setprio 1
	s_waitcnt lgkmcnt(0)
	v_mfma_f32_16x16x32_bf16 v[144:147], v[112:115], v[164:167], v[144:147]
	v_mfma_f32_16x16x32_bf16 v[144:147], v[136:139], v[168:171], v[144:147]
	v_mfma_f32_16x16x32_bf16 v[120:123], v[112:115], v[172:175], v[120:123]
	v_mfma_f32_16x16x32_bf16 v[120:123], v[136:139], v[176:179], v[120:123]
	v_mfma_f32_16x16x32_bf16 v[92:95], v[112:115], v[180:183], v[92:95]
	v_mfma_f32_16x16x32_bf16 v[92:95], v[136:139], v[184:187], v[92:95]
	v_mfma_f32_16x16x32_bf16 v[68:71], v[112:115], v[188:191], v[68:71]
	v_mfma_f32_16x16x32_bf16 v[68:71], v[136:139], v[192:195], v[68:71]
	v_mfma_f32_16x16x32_bf16 v[64:67], v[148:151], v[188:191], v[64:67]
	v_mfma_f32_16x16x32_bf16 v[64:67], v[160:163], v[192:195], v[64:67]
	v_mfma_f32_16x16x32_bf16 v[88:91], v[148:151], v[180:183], v[88:91]
	v_mfma_f32_16x16x32_bf16 v[88:91], v[160:163], v[184:187], v[88:91]
	v_mfma_f32_16x16x32_bf16 v[116:119], v[148:151], v[172:175], v[116:119]
	v_mfma_f32_16x16x32_bf16 v[116:119], v[160:163], v[176:179], v[116:119]
	v_mfma_f32_16x16x32_bf16 v[140:143], v[148:151], v[164:167], v[140:143]
	s_barrier
	v_mfma_f32_16x16x32_bf16 v[140:143], v[160:163], v[168:171], v[140:143]
	s_setprio 0
	s_add_u32 s92, s58, 0x2000
	ds_read_b128 v[164:167], v214 offset:16384
	ds_read_b128 v[168:171], v214 offset:17408
	ds_read_b128 v[172:175], v214 offset:18432
	ds_read_b128 v[176:179], v214 offset:19456
	ds_read_b128 v[180:183], v214 offset:20480
	ds_read_b128 v[184:187], v214 offset:21504
	ds_read_b128 v[188:191], v214 offset:22528
	ds_read_b128 v[192:195], v214 offset:23552
	s_mov_b32 m0, s47
	s_nop 0
	global_load_lds_dwordx4 v210, s[58:59]
	s_addc_u32 s93, s59, 0
	s_mov_b32 m0, s49
	s_nop 0
	global_load_lds_dwordx4 v210, s[92:93]
	s_add_u32 s92, s58, 0x4000
	s_addc_u32 s93, s59, 0
	s_mov_b32 m0, s61
	s_nop 0
	global_load_lds_dwordx4 v210, s[92:93]
	s_add_u32 s92, s58, 0x6000
	s_addc_u32 s93, s59, 0
	s_mov_b32 m0, s62
	s_nop 0
	global_load_lds_dwordx4 v210, s[92:93]
	s_add_u32 s92, s2, 0x2000
	s_mov_b32 m0, s60
	s_nop 0
	global_load_lds_dwordx4 v210, s[2:3]
	s_addc_u32 s93, s3, 0
	s_mov_b32 m0, s63
	s_nop 0
	global_load_lds_dwordx4 v210, s[92:93]
	s_waitcnt vmcnt(8)
	s_waitcnt lgkmcnt(0)
	s_barrier
	s_setprio 1
	s_waitcnt lgkmcnt(7)
	s_waitcnt lgkmcnt(0)
	v_mfma_f32_16x16x32_bf16 v[60:63], v[72:75], v[164:167], v[60:63]
	v_mfma_f32_16x16x32_bf16 v[60:63], v[84:87], v[168:171], v[60:63]
	v_mfma_f32_16x16x32_bf16 v[44:47], v[72:75], v[172:175], v[44:47]
	v_mfma_f32_16x16x32_bf16 v[44:47], v[84:87], v[176:179], v[44:47]
	v_mfma_f32_16x16x32_bf16 v[28:31], v[72:75], v[180:183], v[28:31]
	v_mfma_f32_16x16x32_bf16 v[28:31], v[84:87], v[184:187], v[28:31]
	v_mfma_f32_16x16x32_bf16 v[12:15], v[72:75], v[188:191], v[12:15]
	v_mfma_f32_16x16x32_bf16 v[12:15], v[84:87], v[192:195], v[12:15]
	v_mfma_f32_16x16x32_bf16 v[8:11], v[96:99], v[188:191], v[8:11]
	v_mfma_f32_16x16x32_bf16 v[8:11], v[108:111], v[192:195], v[8:11]
	v_mfma_f32_16x16x32_bf16 v[24:27], v[96:99], v[180:183], v[24:27]
	v_mfma_f32_16x16x32_bf16 v[24:27], v[108:111], v[184:187], v[24:27]
	v_mfma_f32_16x16x32_bf16 v[40:43], v[96:99], v[172:175], v[40:43]
	v_mfma_f32_16x16x32_bf16 v[40:43], v[108:111], v[176:179], v[40:43]
	v_mfma_f32_16x16x32_bf16 v[56:59], v[96:99], v[164:167], v[56:59]
	v_mfma_f32_16x16x32_bf16 v[56:59], v[108:111], v[168:171], v[56:59]
	s_setprio 0
	s_setprio 1
	s_waitcnt lgkmcnt(0)
	v_mfma_f32_16x16x32_bf16 v[52:55], v[112:115], v[164:167], v[52:55]
	v_mfma_f32_16x16x32_bf16 v[52:55], v[136:139], v[168:171], v[52:55]
	v_mfma_f32_16x16x32_bf16 v[36:39], v[112:115], v[172:175], v[36:39]
	v_mfma_f32_16x16x32_bf16 v[36:39], v[136:139], v[176:179], v[36:39]
	v_mfma_f32_16x16x32_bf16 v[20:23], v[112:115], v[180:183], v[20:23]
	v_mfma_f32_16x16x32_bf16 v[20:23], v[136:139], v[184:187], v[20:23]
	v_mfma_f32_16x16x32_bf16 v[4:7], v[112:115], v[188:191], v[4:7]
	v_mfma_f32_16x16x32_bf16 v[4:7], v[136:139], v[192:195], v[4:7]
	v_mfma_f32_16x16x32_bf16 v[0:3], v[148:151], v[188:191], v[0:3]
	v_mfma_f32_16x16x32_bf16 v[0:3], v[160:163], v[192:195], v[0:3]
	v_mfma_f32_16x16x32_bf16 v[16:19], v[148:151], v[180:183], v[16:19]
	v_mfma_f32_16x16x32_bf16 v[16:19], v[160:163], v[184:187], v[16:19]
	v_mfma_f32_16x16x32_bf16 v[32:35], v[148:151], v[172:175], v[32:35]
	v_mfma_f32_16x16x32_bf16 v[32:35], v[160:163], v[176:179], v[32:35]
	v_mfma_f32_16x16x32_bf16 v[48:51], v[148:151], v[164:167], v[48:51]
	s_barrier
	v_mfma_f32_16x16x32_bf16 v[48:51], v[160:163], v[168:171], v[48:51]
	s_setprio 0
	ds_read_b128 v[72:75], v124
	ds_read_b128 v[84:87], v124 offset:1024
	ds_read_b128 v[96:99], v124 offset:2048
	ds_read_b128 v[108:111], v124 offset:3072
	ds_read_b128 v[112:115], v125
	ds_read_b128 v[136:139], v125 offset:1024
	ds_read_b128 v[148:151], v125 offset:2048
	ds_read_b128 v[160:163], v125 offset:3072
	ds_read_b128 v[164:167], v214 offset:32768
	ds_read_b128 v[168:171], v214 offset:33792
	ds_read_b128 v[172:175], v214 offset:34816
	ds_read_b128 v[176:179], v214 offset:35840
	ds_read_b128 v[180:183], v214 offset:36864
	ds_read_b128 v[184:187], v214 offset:37888
	ds_read_b128 v[188:191], v214 offset:38912
	ds_read_b128 v[192:195], v214 offset:39936
	s_add_u32 s92, s2, 0x4000
	s_addc_u32 s93, s3, 0
	s_mov_b32 m0, s64
	s_nop 0
	global_load_lds_dwordx4 v210, s[92:93]
	s_add_u32 s92, s2, 0x6000
	s_addc_u32 s93, s3, 0
	s_mov_b32 m0, s65
	s_nop 0
	global_load_lds_dwordx4 v210, s[92:93]
	s_waitcnt vmcnt(8)
	s_waitcnt lgkmcnt(0)
	s_barrier
	s_setprio 1
	s_waitcnt lgkmcnt(7)
	v_mfma_f32_16x16x32_bf16 v[156:159], v[72:75], v[164:167], v[156:159]
	v_mfma_f32_16x16x32_bf16 v[152:155], v[96:99], v[164:167], v[152:155]
	s_waitcnt lgkmcnt(5)
	v_mfma_f32_16x16x32_bf16 v[130:133], v[72:75], v[172:175], v[132:135]
	v_mfma_f32_16x16x32_bf16 v[126:129], v[96:99], v[172:175], v[126:129]
	s_waitcnt lgkmcnt(3)
	v_mfma_f32_16x16x32_bf16 v[104:107], v[72:75], v[180:183], v[104:107]
	v_mfma_f32_16x16x32_bf16 v[100:103], v[96:99], v[180:183], v[100:103]
	s_waitcnt lgkmcnt(1)
	v_mfma_f32_16x16x32_bf16 v[80:83], v[72:75], v[188:191], v[80:83]
	v_mfma_f32_16x16x32_bf16 v[76:79], v[96:99], v[188:191], v[76:79]
	v_mfma_f32_16x16x32_bf16 v[156:159], v[84:87], v[168:171], v[156:159]
	v_mfma_f32_16x16x32_bf16 v[152:155], v[108:111], v[168:171], v[152:155]
	v_mfma_f32_16x16x32_bf16 v[132:135], v[84:87], v[176:179], v[130:133]
	v_mfma_f32_16x16x32_bf16 v[128:131], v[108:111], v[176:179], v[126:129]
	v_mfma_f32_16x16x32_bf16 v[104:107], v[84:87], v[184:187], v[104:107]
	v_mfma_f32_16x16x32_bf16 v[100:103], v[108:111], v[184:187], v[100:103]
	s_waitcnt lgkmcnt(0)
	v_mfma_f32_16x16x32_bf16 v[80:83], v[84:87], v[192:195], v[80:83]
	v_mfma_f32_16x16x32_bf16 v[76:79], v[108:111], v[192:195], v[76:79]
	s_setprio 0
	s_setprio 1
	s_waitcnt lgkmcnt(0)
	v_mfma_f32_16x16x32_bf16 v[144:147], v[112:115], v[164:167], v[144:147]
	v_mfma_f32_16x16x32_bf16 v[144:147], v[136:139], v[168:171], v[144:147]
	v_mfma_f32_16x16x32_bf16 v[120:123], v[112:115], v[172:175], v[120:123]
	v_mfma_f32_16x16x32_bf16 v[120:123], v[136:139], v[176:179], v[120:123]
	v_mfma_f32_16x16x32_bf16 v[92:95], v[112:115], v[180:183], v[92:95]
	v_mfma_f32_16x16x32_bf16 v[92:95], v[136:139], v[184:187], v[92:95]
	v_mfma_f32_16x16x32_bf16 v[68:71], v[112:115], v[188:191], v[68:71]
	v_mfma_f32_16x16x32_bf16 v[68:71], v[136:139], v[192:195], v[68:71]
	v_mfma_f32_16x16x32_bf16 v[64:67], v[148:151], v[188:191], v[64:67]
	v_mfma_f32_16x16x32_bf16 v[64:67], v[160:163], v[192:195], v[64:67]
	v_mfma_f32_16x16x32_bf16 v[88:91], v[148:151], v[180:183], v[88:91]
	v_mfma_f32_16x16x32_bf16 v[88:91], v[160:163], v[184:187], v[88:91]
	v_mfma_f32_16x16x32_bf16 v[116:119], v[148:151], v[172:175], v[116:119]
	v_mfma_f32_16x16x32_bf16 v[116:119], v[160:163], v[176:179], v[116:119]
	v_mfma_f32_16x16x32_bf16 v[140:143], v[148:151], v[164:167], v[140:143]
	s_barrier
	v_mfma_f32_16x16x32_bf16 v[140:143], v[160:163], v[168:171], v[140:143]
	s_setprio 0
	ds_read_b128 v[164:167], v214 offset:49152
	ds_read_b128 v[168:171], v214 offset:50176
	ds_read_b128 v[172:175], v214 offset:51200
	ds_read_b128 v[176:179], v214 offset:52224
	ds_read_b128 v[180:183], v214 offset:53248
	ds_read_b128 v[184:187], v214 offset:54272
	ds_read_b128 v[188:191], v214 offset:55296
	ds_read_b128 v[192:195], v214 offset:56320
	s_mov_b32 m0, s69
	s_nop 0
	global_load_lds_dwordx4 v210, s[52:53]
	s_add_u32 s52, s58, 0xa000
	s_addc_u32 s53, s59, 0
	s_mov_b32 m0, s70
	s_nop 0
	global_load_lds_dwordx4 v210, s[52:53]
	s_add_u32 s52, s58, 0xc000
	s_addc_u32 s53, s59, 0
	s_mov_b32 m0, s73
	s_nop 0
	global_load_lds_dwordx4 v210, s[52:53]
	s_add_u32 s52, s58, 0xe000
	s_addc_u32 s53, s59, 0
	s_mov_b32 m0, s74
	s_nop 0
	global_load_lds_dwordx4 v210, s[52:53]
	s_add_u32 s2, s2, 0xa000
	s_mov_b32 m0, s71
	s_nop 0
	global_load_lds_dwordx4 v210, s[56:57]
	s_addc_u32 s3, s3, 0
	s_mov_b32 m0, s72
	s_nop 0
	global_load_lds_dwordx4 v210, s[2:3]
	s_waitcnt vmcnt(8)
	s_waitcnt lgkmcnt(0)
	s_barrier
	s_setprio 1
	s_waitcnt lgkmcnt(7)
	s_waitcnt lgkmcnt(0)
	v_mfma_f32_16x16x32_bf16 v[60:63], v[72:75], v[164:167], v[60:63]
	v_mfma_f32_16x16x32_bf16 v[60:63], v[84:87], v[168:171], v[60:63]
	v_mfma_f32_16x16x32_bf16 v[44:47], v[72:75], v[172:175], v[44:47]
	v_mfma_f32_16x16x32_bf16 v[44:47], v[84:87], v[176:179], v[44:47]
	v_mfma_f32_16x16x32_bf16 v[28:31], v[72:75], v[180:183], v[28:31]
	v_mfma_f32_16x16x32_bf16 v[28:31], v[84:87], v[184:187], v[28:31]
	v_mfma_f32_16x16x32_bf16 v[12:15], v[72:75], v[188:191], v[12:15]
	v_mfma_f32_16x16x32_bf16 v[12:15], v[84:87], v[192:195], v[12:15]
	v_mfma_f32_16x16x32_bf16 v[8:11], v[96:99], v[188:191], v[8:11]
	v_mfma_f32_16x16x32_bf16 v[8:11], v[108:111], v[192:195], v[8:11]
	v_mfma_f32_16x16x32_bf16 v[24:27], v[96:99], v[180:183], v[24:27]
	v_mfma_f32_16x16x32_bf16 v[24:27], v[108:111], v[184:187], v[24:27]
	v_mfma_f32_16x16x32_bf16 v[40:43], v[96:99], v[172:175], v[40:43]
	v_mfma_f32_16x16x32_bf16 v[40:43], v[108:111], v[176:179], v[40:43]
	v_mfma_f32_16x16x32_bf16 v[56:59], v[96:99], v[164:167], v[56:59]
	v_mfma_f32_16x16x32_bf16 v[56:59], v[108:111], v[168:171], v[56:59]
	s_setprio 0
	s_setprio 1
	s_waitcnt lgkmcnt(0)
	v_mfma_f32_16x16x32_bf16 v[52:55], v[112:115], v[164:167], v[52:55]
	v_mfma_f32_16x16x32_bf16 v[52:55], v[136:139], v[168:171], v[52:55]
	v_mfma_f32_16x16x32_bf16 v[36:39], v[112:115], v[172:175], v[36:39]
	v_mfma_f32_16x16x32_bf16 v[36:39], v[136:139], v[176:179], v[36:39]
	s_add_i32 s90, s90, 2
	v_mfma_f32_16x16x32_bf16 v[20:23], v[112:115], v[180:183], v[20:23]
	s_add_u32 s54, s54, 0x10000
	v_mfma_f32_16x16x32_bf16 v[20:23], v[136:139], v[184:187], v[20:23]
	s_addc_u32 s55, s55, 0
	v_mfma_f32_16x16x32_bf16 v[4:7], v[112:115], v[188:191], v[4:7]
	s_add_u32 s88, s88, 0x10000
	v_mfma_f32_16x16x32_bf16 v[4:7], v[136:139], v[192:195], v[4:7]
	s_addc_u32 s89, s89, 0
	v_mfma_f32_16x16x32_bf16 v[0:3], v[148:151], v[188:191], v[0:3]
	s_cmp_gt_u32 s90, 61
	v_mfma_f32_16x16x32_bf16 v[0:3], v[160:163], v[192:195], v[0:3]
	v_mfma_f32_16x16x32_bf16 v[16:19], v[148:151], v[180:183], v[16:19]
	v_mfma_f32_16x16x32_bf16 v[16:19], v[160:163], v[184:187], v[16:19]
	v_mfma_f32_16x16x32_bf16 v[32:35], v[148:151], v[172:175], v[32:35]
	v_mfma_f32_16x16x32_bf16 v[32:35], v[160:163], v[176:179], v[32:35]
	v_mfma_f32_16x16x32_bf16 v[48:51], v[148:151], v[164:167], v[48:51]
	s_barrier
	v_mfma_f32_16x16x32_bf16 v[48:51], v[160:163], v[168:171], v[48:51]
	s_setprio 0
	s_cbranch_scc0 .LBB0_1406
	s_nop 7
	s_and_b64 vcc, exec, s[12:13]
	s_cbranch_vccz .LBB0_1409
	s_barrier

.LBB0_1505:
	ds_read_b128 v[128:131], v156
	ds_read_b128 v[132:135], v156 offset:1024
	ds_read_b128 v[136:139], v156 offset:2048
	ds_read_b128 v[140:143], v156 offset:3072
	ds_read_b128 v[146:149], v157
	ds_read_b128 v[162:165], v157 offset:1024
	ds_read_b128 v[166:169], v157 offset:2048
	ds_read_b128 v[170:173], v157 offset:3072
	s_add_u32 s2, s52, 0x10000
	s_addc_u32 s3, s53, 0
	s_cmp_eq_u32 s96, 60
	s_cselect_b32 s58, s92, s2
	s_cselect_b32 s59, s45, s3
	s_cselect_b32 s64, s93, s54
	s_cselect_b32 s65, s43, s55
	s_add_u32 s60, s58, 0x8000
	s_addc_u32 s61, s59, 0
	ds_read_b128 v[174:177], v158
	ds_read_b128 v[178:181], v158 offset:1024
	ds_read_b128 v[182:185], v158 offset:2048
	ds_read_b128 v[186:189], v158 offset:3072
	ds_read_b128 v[190:193], v158 offset:4096
	ds_read_b128 v[194:197], v158 offset:5120
	ds_read_b128 v[198:201], v158 offset:6144
	ds_read_b128 v[202:205], v158 offset:7168
	s_add_u32 s12, s52, 0xc000
	s_addc_u32 s13, s53, 0
	s_mov_b32 m0, s81
	s_nop 0
	global_load_lds_dwordx4 v154, s[12:13]
	s_add_u32 s12, s52, 0xe000
	s_addc_u32 s13, s53, 0
	s_mov_b32 m0, s82
	s_nop 0
	global_load_lds_dwordx4 v154, s[12:13]
	s_waitcnt vmcnt(8)
	s_waitcnt lgkmcnt(0)
	s_add_u32 s52, s64, 0x8000
	s_addc_u32 s53, s65, 0
	s_barrier
	s_setprio 1
	s_waitcnt lgkmcnt(7)
	s_waitcnt lgkmcnt(0)
	v_mfma_f32_16x16x32_bf16 v[116:119], v[128:131], v[174:177], v[116:119]
	v_mfma_f32_16x16x32_bf16 v[116:119], v[132:135], v[178:181], v[116:119]
	v_mfma_f32_16x16x32_bf16 v[100:103], v[128:131], v[182:185], v[100:103]
	v_mfma_f32_16x16x32_bf16 v[100:103], v[132:135], v[186:189], v[100:103]
	v_mfma_f32_16x16x32_bf16 v[92:95], v[128:131], v[190:193], v[92:95]
	v_mfma_f32_16x16x32_bf16 v[92:95], v[132:135], v[194:197], v[92:95]
	v_mfma_f32_16x16x32_bf16 v[76:79], v[128:131], v[198:201], v[76:79]
	v_mfma_f32_16x16x32_bf16 v[76:79], v[132:135], v[202:205], v[76:79]
	v_mfma_f32_16x16x32_bf16 v[72:75], v[136:139], v[198:201], v[72:75]
	v_mfma_f32_16x16x32_bf16 v[72:75], v[140:143], v[202:205], v[72:75]
	v_mfma_f32_16x16x32_bf16 v[88:91], v[136:139], v[190:193], v[88:91]
	v_mfma_f32_16x16x32_bf16 v[88:91], v[140:143], v[194:197], v[88:91]
	v_mfma_f32_16x16x32_bf16 v[96:99], v[136:139], v[182:185], v[96:99]
	v_mfma_f32_16x16x32_bf16 v[96:99], v[140:143], v[186:189], v[96:99]
	v_mfma_f32_16x16x32_bf16 v[112:115], v[136:139], v[174:177], v[112:115]
	v_mfma_f32_16x16x32_bf16 v[112:115], v[140:143], v[178:181], v[112:115]
	s_setprio 0
	s_setprio 1
	s_waitcnt lgkmcnt(0)
	v_mfma_f32_16x16x32_bf16 v[124:127], v[146:149], v[174:177], v[124:127]
	v_mfma_f32_16x16x32_bf16 v[124:127], v[162:165], v[178:181], v[124:127]
	v_mfma_f32_16x16x32_bf16 v[108:111], v[146:149], v[182:185], v[108:111]
	v_mfma_f32_16x16x32_bf16 v[108:111], v[162:165], v[186:189], v[108:111]
	v_mfma_f32_16x16x32_bf16 v[84:87], v[146:149], v[190:193], v[84:87]
	v_mfma_f32_16x16x32_bf16 v[84:87], v[162:165], v[194:197], v[84:87]
	v_mfma_f32_16x16x32_bf16 v[68:71], v[146:149], v[198:201], v[68:71]
	v_mfma_f32_16x16x32_bf16 v[68:71], v[162:165], v[202:205], v[68:71]
	v_mfma_f32_16x16x32_bf16 v[64:67], v[166:169], v[198:201], v[64:67]
	v_mfma_f32_16x16x32_bf16 v[64:67], v[170:173], v[202:205], v[64:67]
	v_mfma_f32_16x16x32_bf16 v[80:83], v[166:169], v[190:193], v[80:83]
	v_mfma_f32_16x16x32_bf16 v[80:83], v[170:173], v[194:197], v[80:83]
	v_mfma_f32_16x16x32_bf16 v[104:107], v[166:169], v[182:185], v[104:107]
	v_mfma_f32_16x16x32_bf16 v[104:107], v[170:173], v[186:189], v[104:107]
	v_mfma_f32_16x16x32_bf16 v[120:123], v[166:169], v[174:177], v[120:123]
	s_barrier
	v_mfma_f32_16x16x32_bf16 v[120:123], v[170:173], v[178:181], v[120:123]
	s_setprio 0
	s_add_u32 s12, s64, 0x2000
	ds_read_b128 v[174:177], v158 offset:16384
	ds_read_b128 v[178:181], v158 offset:17408
	ds_read_b128 v[182:185], v158 offset:18432
	ds_read_b128 v[186:189], v158 offset:19456
	ds_read_b128 v[190:193], v158 offset:20480
	ds_read_b128 v[194:197], v158 offset:21504
	ds_read_b128 v[198:201], v158 offset:22528
	ds_read_b128 v[202:205], v158 offset:23552
	s_mov_b32 m0, s57
	s_nop 0
	global_load_lds_dwordx4 v154, s[64:65]
	s_addc_u32 s13, s65, 0
	s_mov_b32 m0, s67
	s_nop 0
	global_load_lds_dwordx4 v154, s[12:13]
	s_add_u32 s12, s64, 0x4000
	s_addc_u32 s13, s65, 0
	s_mov_b32 m0, s68
	s_nop 0
	global_load_lds_dwordx4 v154, s[12:13]
	s_add_u32 s12, s64, 0x6000
	s_addc_u32 s13, s65, 0
	s_mov_b32 m0, s69
	s_nop 0
	global_load_lds_dwordx4 v154, s[12:13]
	s_add_u32 s12, s58, 0x2000
	s_mov_b32 m0, s66
	s_nop 0
	global_load_lds_dwordx4 v154, s[58:59]
	s_addc_u32 s13, s59, 0
	s_mov_b32 m0, s70
	s_nop 0
	global_load_lds_dwordx4 v154, s[12:13]
	s_waitcnt vmcnt(8)
	s_waitcnt lgkmcnt(0)
	s_barrier
	s_setprio 1
	s_waitcnt lgkmcnt(7)
	s_waitcnt lgkmcnt(0)
	v_mfma_f32_16x16x32_bf16 v[60:63], v[128:131], v[174:177], v[60:63]
	v_mfma_f32_16x16x32_bf16 v[60:63], v[132:135], v[178:181], v[60:63]
	v_mfma_f32_16x16x32_bf16 v[44:47], v[128:131], v[182:185], v[44:47]
	v_mfma_f32_16x16x32_bf16 v[44:47], v[132:135], v[186:189], v[44:47]
	v_mfma_f32_16x16x32_bf16 v[28:31], v[128:131], v[190:193], v[28:31]
	v_mfma_f32_16x16x32_bf16 v[28:31], v[132:135], v[194:197], v[28:31]
	v_mfma_f32_16x16x32_bf16 v[12:15], v[128:131], v[198:201], v[12:15]
	v_mfma_f32_16x16x32_bf16 v[12:15], v[132:135], v[202:205], v[12:15]
	v_mfma_f32_16x16x32_bf16 v[8:11], v[136:139], v[198:201], v[8:11]
	v_mfma_f32_16x16x32_bf16 v[8:11], v[140:143], v[202:205], v[8:11]
	v_mfma_f32_16x16x32_bf16 v[24:27], v[136:139], v[190:193], v[24:27]
	v_mfma_f32_16x16x32_bf16 v[24:27], v[140:143], v[194:197], v[24:27]
	v_mfma_f32_16x16x32_bf16 v[40:43], v[136:139], v[182:185], v[40:43]
	v_mfma_f32_16x16x32_bf16 v[40:43], v[140:143], v[186:189], v[40:43]
	v_mfma_f32_16x16x32_bf16 v[56:59], v[136:139], v[174:177], v[56:59]
	v_mfma_f32_16x16x32_bf16 v[56:59], v[140:143], v[178:181], v[56:59]
	s_setprio 0
	s_setprio 1
	s_waitcnt lgkmcnt(0)
	v_mfma_f32_16x16x32_bf16 v[52:55], v[146:149], v[174:177], v[52:55]
	v_mfma_f32_16x16x32_bf16 v[52:55], v[162:165], v[178:181], v[52:55]
	v_mfma_f32_16x16x32_bf16 v[36:39], v[146:149], v[182:185], v[36:39]
	v_mfma_f32_16x16x32_bf16 v[36:39], v[162:165], v[186:189], v[36:39]
	v_mfma_f32_16x16x32_bf16 v[20:23], v[146:149], v[190:193], v[20:23]
	v_mfma_f32_16x16x32_bf16 v[20:23], v[162:165], v[194:197], v[20:23]
	v_mfma_f32_16x16x32_bf16 v[4:7], v[146:149], v[198:201], v[4:7]
	v_mfma_f32_16x16x32_bf16 v[4:7], v[162:165], v[202:205], v[4:7]
	v_mfma_f32_16x16x32_bf16 v[0:3], v[166:169], v[198:201], v[0:3]
	v_mfma_f32_16x16x32_bf16 v[0:3], v[170:173], v[202:205], v[0:3]
	v_mfma_f32_16x16x32_bf16 v[16:19], v[166:169], v[190:193], v[16:19]
	v_mfma_f32_16x16x32_bf16 v[16:19], v[170:173], v[194:197], v[16:19]
	v_mfma_f32_16x16x32_bf16 v[32:35], v[166:169], v[182:185], v[32:35]
	v_mfma_f32_16x16x32_bf16 v[32:35], v[170:173], v[186:189], v[32:35]
	v_mfma_f32_16x16x32_bf16 v[48:51], v[166:169], v[174:177], v[48:51]
	s_barrier
	v_mfma_f32_16x16x32_bf16 v[48:51], v[170:173], v[178:181], v[48:51]
	s_setprio 0
	ds_read_b128 v[128:131], v144
	ds_read_b128 v[132:135], v144 offset:1024
	ds_read_b128 v[136:139], v144 offset:2048
	ds_read_b128 v[140:143], v144 offset:3072
	ds_read_b128 v[146:149], v150
	ds_read_b128 v[162:165], v150 offset:1024
	ds_read_b128 v[166:169], v150 offset:2048
	ds_read_b128 v[170:173], v150 offset:3072
	ds_read_b128 v[174:177], v158 offset:32768
	ds_read_b128 v[178:181], v158 offset:33792
	ds_read_b128 v[182:185], v158 offset:34816
	ds_read_b128 v[186:189], v158 offset:35840
	ds_read_b128 v[190:193], v158 offset:36864
	ds_read_b128 v[194:197], v158 offset:37888
	ds_read_b128 v[198:201], v158 offset:38912
	ds_read_b128 v[202:205], v158 offset:39936
	s_add_u32 s12, s58, 0x4000
	s_addc_u32 s13, s59, 0
	s_mov_b32 m0, s71
	s_nop 0
	global_load_lds_dwordx4 v154, s[12:13]
	s_add_u32 s12, s58, 0x6000
	s_addc_u32 s13, s59, 0
	s_mov_b32 m0, s72
	s_nop 0
	global_load_lds_dwordx4 v154, s[12:13]
	s_waitcnt vmcnt(8)
	s_waitcnt lgkmcnt(0)
	s_barrier
	s_setprio 1
	s_waitcnt lgkmcnt(7)
	s_waitcnt lgkmcnt(0)
	v_mfma_f32_16x16x32_bf16 v[116:119], v[128:131], v[174:177], v[116:119]
	v_mfma_f32_16x16x32_bf16 v[116:119], v[132:135], v[178:181], v[116:119]
	v_mfma_f32_16x16x32_bf16 v[100:103], v[128:131], v[182:185], v[100:103]
	v_mfma_f32_16x16x32_bf16 v[100:103], v[132:135], v[186:189], v[100:103]
	v_mfma_f32_16x16x32_bf16 v[92:95], v[128:131], v[190:193], v[92:95]
	v_mfma_f32_16x16x32_bf16 v[92:95], v[132:135], v[194:197], v[92:95]
	v_mfma_f32_16x16x32_bf16 v[76:79], v[128:131], v[198:201], v[76:79]
	v_mfma_f32_16x16x32_bf16 v[76:79], v[132:135], v[202:205], v[76:79]
	v_mfma_f32_16x16x32_bf16 v[72:75], v[136:139], v[198:201], v[72:75]
	v_mfma_f32_16x16x32_bf16 v[72:75], v[140:143], v[202:205], v[72:75]
	v_mfma_f32_16x16x32_bf16 v[88:91], v[136:139], v[190:193], v[88:91]
	v_mfma_f32_16x16x32_bf16 v[88:91], v[140:143], v[194:197], v[88:91]
	v_mfma_f32_16x16x32_bf16 v[96:99], v[136:139], v[182:185], v[96:99]
	v_mfma_f32_16x16x32_bf16 v[96:99], v[140:143], v[186:189], v[96:99]
	v_mfma_f32_16x16x32_bf16 v[112:115], v[136:139], v[174:177], v[112:115]
	v_mfma_f32_16x16x32_bf16 v[112:115], v[140:143], v[178:181], v[112:115]
	s_setprio 0
	s_setprio 1
	s_waitcnt lgkmcnt(0)
	v_mfma_f32_16x16x32_bf16 v[124:127], v[146:149], v[174:177], v[124:127]
	v_mfma_f32_16x16x32_bf16 v[124:127], v[162:165], v[178:181], v[124:127]
	v_mfma_f32_16x16x32_bf16 v[108:111], v[146:149], v[182:185], v[108:111]
	v_mfma_f32_16x16x32_bf16 v[108:111], v[162:165], v[186:189], v[108:111]
	v_mfma_f32_16x16x32_bf16 v[84:87], v[146:149], v[190:193], v[84:87]
	v_mfma_f32_16x16x32_bf16 v[84:87], v[162:165], v[194:197], v[84:87]
	v_mfma_f32_16x16x32_bf16 v[68:71], v[146:149], v[198:201], v[68:71]
	v_mfma_f32_16x16x32_bf16 v[68:71], v[162:165], v[202:205], v[68:71]
	v_mfma_f32_16x16x32_bf16 v[64:67], v[166:169], v[198:201], v[64:67]
	v_mfma_f32_16x16x32_bf16 v[64:67], v[170:173], v[202:205], v[64:67]
	v_mfma_f32_16x16x32_bf16 v[80:83], v[166:169], v[190:193], v[80:83]
	v_mfma_f32_16x16x32_bf16 v[80:83], v[170:173], v[194:197], v[80:83]
	v_mfma_f32_16x16x32_bf16 v[104:107], v[166:169], v[182:185], v[104:107]
	v_mfma_f32_16x16x32_bf16 v[104:107], v[170:173], v[186:189], v[104:107]
	v_mfma_f32_16x16x32_bf16 v[120:123], v[166:169], v[174:177], v[120:123]
	s_barrier
	v_mfma_f32_16x16x32_bf16 v[120:123], v[170:173], v[178:181], v[120:123]
	s_setprio 0
	s_add_u32 s12, s64, 0xa000
	ds_read_b128 v[174:177], v158 offset:49152
	ds_read_b128 v[178:181], v158 offset:50176
	ds_read_b128 v[182:185], v158 offset:51200
	ds_read_b128 v[186:189], v158 offset:52224
	ds_read_b128 v[190:193], v158 offset:53248
	ds_read_b128 v[194:197], v158 offset:54272
	ds_read_b128 v[198:201], v158 offset:55296
	ds_read_b128 v[202:205], v158 offset:56320
	s_mov_b32 m0, s75
	s_nop 0
	global_load_lds_dwordx4 v154, s[52:53]
	s_addc_u32 s13, s65, 0
	s_mov_b32 m0, s76
	s_nop 0
	global_load_lds_dwordx4 v154, s[12:13]
	s_add_u32 s12, s64, 0xc000
	s_addc_u32 s13, s65, 0
	s_mov_b32 m0, s79
	s_nop 0
	global_load_lds_dwordx4 v154, s[12:13]
	s_add_u32 s12, s64, 0xe000
	s_addc_u32 s13, s65, 0
	s_mov_b32 m0, s80
	s_nop 0
	global_load_lds_dwordx4 v154, s[12:13]
	s_add_u32 s12, s58, 0xa000
	s_mov_b32 m0, s77
	s_nop 0
	global_load_lds_dwordx4 v154, s[60:61]
	s_addc_u32 s13, s59, 0
	s_mov_b32 m0, s78
	s_nop 0
	global_load_lds_dwordx4 v154, s[12:13]
	s_waitcnt vmcnt(8)
	s_waitcnt lgkmcnt(0)
	s_barrier
	s_setprio 1
	s_waitcnt lgkmcnt(7)
	s_waitcnt lgkmcnt(0)
	v_mfma_f32_16x16x32_bf16 v[60:63], v[128:131], v[174:177], v[60:63]
	v_mfma_f32_16x16x32_bf16 v[60:63], v[132:135], v[178:181], v[60:63]
	v_mfma_f32_16x16x32_bf16 v[44:47], v[128:131], v[182:185], v[44:47]
	v_mfma_f32_16x16x32_bf16 v[44:47], v[132:135], v[186:189], v[44:47]
	v_mfma_f32_16x16x32_bf16 v[28:31], v[128:131], v[190:193], v[28:31]
	v_mfma_f32_16x16x32_bf16 v[28:31], v[132:135], v[194:197], v[28:31]
	v_mfma_f32_16x16x32_bf16 v[12:15], v[128:131], v[198:201], v[12:15]
	v_mfma_f32_16x16x32_bf16 v[12:15], v[132:135], v[202:205], v[12:15]
	v_mfma_f32_16x16x32_bf16 v[8:11], v[136:139], v[198:201], v[8:11]
	v_mfma_f32_16x16x32_bf16 v[8:11], v[140:143], v[202:205], v[8:11]
	v_mfma_f32_16x16x32_bf16 v[24:27], v[136:139], v[190:193], v[24:27]
	v_mfma_f32_16x16x32_bf16 v[24:27], v[140:143], v[194:197], v[24:27]
	v_mfma_f32_16x16x32_bf16 v[40:43], v[136:139], v[182:185], v[40:43]
	v_mfma_f32_16x16x32_bf16 v[40:43], v[140:143], v[186:189], v[40:43]
	v_mfma_f32_16x16x32_bf16 v[56:59], v[136:139], v[174:177], v[56:59]
	v_mfma_f32_16x16x32_bf16 v[56:59], v[140:143], v[178:181], v[56:59]
	s_setprio 0
	s_setprio 1
	s_waitcnt lgkmcnt(0)
	v_mfma_f32_16x16x32_bf16 v[52:55], v[146:149], v[174:177], v[52:55]
	v_mfma_f32_16x16x32_bf16 v[52:55], v[162:165], v[178:181], v[52:55]
	v_mfma_f32_16x16x32_bf16 v[36:39], v[146:149], v[182:185], v[36:39]
	v_mfma_f32_16x16x32_bf16 v[36:39], v[162:165], v[186:189], v[36:39]
	s_add_i32 s96, s96, 2
	v_mfma_f32_16x16x32_bf16 v[20:23], v[146:149], v[190:193], v[20:23]
	s_add_u32 s54, s54, 0x10000
	v_mfma_f32_16x16x32_bf16 v[20:23], v[162:165], v[194:197], v[20:23]
	s_addc_u32 s55, s55, 0
	v_mfma_f32_16x16x32_bf16 v[4:7], v[146:149], v[198:201], v[4:7]
	s_cmp_gt_u32 s96, 61
	v_mfma_f32_16x16x32_bf16 v[4:7], v[162:165], v[202:205], v[4:7]
	s_mov_b64 s[52:53], s[2:3]
	v_mfma_f32_16x16x32_bf16 v[0:3], v[166:169], v[198:201], v[0:3]
	v_mfma_f32_16x16x32_bf16 v[0:3], v[170:173], v[202:205], v[0:3]
	v_mfma_f32_16x16x32_bf16 v[16:19], v[166:169], v[190:193], v[16:19]
	v_mfma_f32_16x16x32_bf16 v[16:19], v[170:173], v[194:197], v[16:19]
	v_mfma_f32_16x16x32_bf16 v[32:35], v[166:169], v[182:185], v[32:35]
	v_mfma_f32_16x16x32_bf16 v[32:35], v[170:173], v[186:189], v[32:35]
	v_mfma_f32_16x16x32_bf16 v[48:51], v[166:169], v[174:177], v[48:51]
	s_barrier
	v_mfma_f32_16x16x32_bf16 v[48:51], v[170:173], v[178:181], v[48:51]
	s_setprio 0
	s_cbranch_scc0 .LBB0_1505
	s_nop 7
	s_and_b64 vcc, exec, s[40:41]
	s_cbranch_vccz .LBB0_1508
	s_barrier

.LBB0_1539:
	ds_read_b128 v[128:131], v138
	ds_read_b128 v[132:135], v138 offset:1024
	ds_read_b128 v[144:147], v138 offset:2048
	ds_read_b128 v[148:151], v138 offset:3072
	ds_read_b128 v[152:155], v139
	ds_read_b128 v[156:159], v139 offset:1024
	ds_read_b128 v[160:163], v139 offset:2048
	ds_read_b128 v[164:167], v139 offset:3072
	s_add_u32 s2, s52, 0x10000
	s_addc_u32 s3, s53, 0
	s_cmp_eq_u32 s83, 60
	s_cselect_b32 s46, s79, s2
	s_cselect_b32 s47, s39, s3
	s_cselect_b32 s56, s80, s81
	s_cselect_b32 s57, s15, s82
	s_add_u32 s48, s46, 0x8000
	s_addc_u32 s49, s47, 0
	ds_read_b128 v[168:171], v140
	ds_read_b128 v[172:175], v140 offset:1024
	ds_read_b128 v[176:179], v140 offset:2048
	ds_read_b128 v[180:183], v140 offset:3072
	ds_read_b128 v[184:187], v140 offset:4096
	ds_read_b128 v[188:191], v140 offset:5120
	ds_read_b128 v[192:195], v140 offset:6144
	ds_read_b128 v[196:199], v140 offset:7168
	s_add_u32 s88, s52, 0xc000
	s_addc_u32 s89, s53, 0
	s_mov_b32 m0, s74
	s_nop 0
	global_load_lds_dwordx4 v136, s[88:89]
	s_add_u32 s52, s52, 0xe000
	s_addc_u32 s53, s53, 0
	s_mov_b32 m0, s75
	s_nop 0
	global_load_lds_dwordx4 v136, s[52:53]
	s_waitcnt vmcnt(8)
	s_waitcnt lgkmcnt(0)
	s_add_u32 s52, s56, 0x8000
	s_addc_u32 s53, s57, 0
	s_barrier
	s_setprio 1
	s_waitcnt lgkmcnt(7)
	s_waitcnt lgkmcnt(0)
	v_mfma_f32_16x16x32_bf16 v[120:123], v[128:131], v[168:171], v[120:123]
	v_mfma_f32_16x16x32_bf16 v[120:123], v[132:135], v[172:175], v[120:123]
	v_mfma_f32_16x16x32_bf16 v[104:107], v[128:131], v[176:179], v[104:107]
	v_mfma_f32_16x16x32_bf16 v[104:107], v[132:135], v[180:183], v[104:107]
	v_mfma_f32_16x16x32_bf16 v[84:87], v[128:131], v[184:187], v[84:87]
	v_mfma_f32_16x16x32_bf16 v[84:87], v[132:135], v[188:191], v[84:87]
	v_mfma_f32_16x16x32_bf16 v[52:55], v[128:131], v[192:195], v[52:55]
	v_mfma_f32_16x16x32_bf16 v[52:55], v[132:135], v[196:199], v[52:55]
	v_mfma_f32_16x16x32_bf16 v[36:39], v[144:147], v[192:195], v[36:39]
	v_mfma_f32_16x16x32_bf16 v[36:39], v[148:151], v[196:199], v[36:39]
	v_mfma_f32_16x16x32_bf16 v[68:71], v[144:147], v[184:187], v[68:71]
	v_mfma_f32_16x16x32_bf16 v[68:71], v[148:151], v[188:191], v[68:71]
	v_mfma_f32_16x16x32_bf16 v[96:99], v[144:147], v[176:179], v[96:99]
	v_mfma_f32_16x16x32_bf16 v[96:99], v[148:151], v[180:183], v[96:99]
	v_mfma_f32_16x16x32_bf16 v[112:115], v[144:147], v[168:171], v[112:115]
	v_mfma_f32_16x16x32_bf16 v[112:115], v[148:151], v[172:175], v[112:115]
	s_setprio 0
	s_setprio 1
	s_waitcnt lgkmcnt(0)
	v_mfma_f32_16x16x32_bf16 v[124:127], v[152:155], v[168:171], v[124:127]
	v_mfma_f32_16x16x32_bf16 v[124:127], v[156:159], v[172:175], v[124:127]
	v_mfma_f32_16x16x32_bf16 v[108:111], v[152:155], v[176:179], v[108:111]
	v_mfma_f32_16x16x32_bf16 v[108:111], v[156:159], v[180:183], v[108:111]
	v_mfma_f32_16x16x32_bf16 v[88:91], v[152:155], v[184:187], v[88:91]
	v_mfma_f32_16x16x32_bf16 v[88:91], v[156:159], v[188:191], v[88:91]
	v_mfma_f32_16x16x32_bf16 v[56:59], v[152:155], v[192:195], v[56:59]
	v_mfma_f32_16x16x32_bf16 v[56:59], v[156:159], v[196:199], v[56:59]
	v_mfma_f32_16x16x32_bf16 v[40:43], v[160:163], v[192:195], v[40:43]
	v_mfma_f32_16x16x32_bf16 v[40:43], v[164:167], v[196:199], v[40:43]
	v_mfma_f32_16x16x32_bf16 v[72:75], v[160:163], v[184:187], v[72:75]
	v_mfma_f32_16x16x32_bf16 v[72:75], v[164:167], v[188:191], v[72:75]
	v_mfma_f32_16x16x32_bf16 v[100:103], v[160:163], v[176:179], v[100:103]
	v_mfma_f32_16x16x32_bf16 v[100:103], v[164:167], v[180:183], v[100:103]
	v_mfma_f32_16x16x32_bf16 v[116:119], v[160:163], v[168:171], v[116:119]
	s_barrier
	v_mfma_f32_16x16x32_bf16 v[116:119], v[164:167], v[172:175], v[116:119]
	s_setprio 0
	s_add_u32 s88, s56, 0x2000
	ds_read_b128 v[168:171], v140 offset:16384
	ds_read_b128 v[172:175], v140 offset:17408
	ds_read_b128 v[176:179], v140 offset:18432
	ds_read_b128 v[180:183], v140 offset:19456
	ds_read_b128 v[184:187], v140 offset:20480
	ds_read_b128 v[188:191], v140 offset:21504
	ds_read_b128 v[192:195], v140 offset:22528
	ds_read_b128 v[196:199], v140 offset:23552
	s_mov_b32 m0, s41
	s_nop 0
	global_load_lds_dwordx4 v136, s[56:57]
	s_addc_u32 s89, s57, 0
	s_mov_b32 m0, s59
	s_nop 0
	global_load_lds_dwordx4 v136, s[88:89]
	s_add_u32 s88, s56, 0x4000
	s_addc_u32 s89, s57, 0
	s_mov_b32 m0, s60
	s_nop 0
	global_load_lds_dwordx4 v136, s[88:89]
	s_add_u32 s88, s56, 0x6000
	s_addc_u32 s89, s57, 0
	s_mov_b32 m0, s61
	s_nop 0
	global_load_lds_dwordx4 v136, s[88:89]
	s_add_u32 s88, s46, 0x2000
	s_mov_b32 m0, s58
	s_nop 0
	global_load_lds_dwordx4 v136, s[46:47]
	s_addc_u32 s89, s47, 0
	s_mov_b32 m0, s62
	s_nop 0
	global_load_lds_dwordx4 v136, s[88:89]
	s_waitcnt vmcnt(8)
	s_waitcnt lgkmcnt(0)
	s_barrier
	s_setprio 1
	s_waitcnt lgkmcnt(7)
	s_waitcnt lgkmcnt(0)
	v_mfma_f32_16x16x32_bf16 v[92:95], v[128:131], v[168:171], v[92:95]
	v_mfma_f32_16x16x32_bf16 v[92:95], v[132:135], v[172:175], v[92:95]
	v_mfma_f32_16x16x32_bf16 v[60:63], v[128:131], v[176:179], v[60:63]
	v_mfma_f32_16x16x32_bf16 v[60:63], v[132:135], v[180:183], v[60:63]
	v_mfma_f32_16x16x32_bf16 v[28:31], v[128:131], v[184:187], v[28:31]
	v_mfma_f32_16x16x32_bf16 v[28:31], v[132:135], v[188:191], v[28:31]
	v_mfma_f32_16x16x32_bf16 v[12:15], v[128:131], v[192:195], v[12:15]
	v_mfma_f32_16x16x32_bf16 v[12:15], v[132:135], v[196:199], v[12:15]
	v_mfma_f32_16x16x32_bf16 v[8:11], v[144:147], v[192:195], v[8:11]
	v_mfma_f32_16x16x32_bf16 v[8:11], v[148:151], v[196:199], v[8:11]
	v_mfma_f32_16x16x32_bf16 v[24:27], v[144:147], v[184:187], v[24:27]
	v_mfma_f32_16x16x32_bf16 v[24:27], v[148:151], v[188:191], v[24:27]
	v_mfma_f32_16x16x32_bf16 v[48:51], v[144:147], v[176:179], v[48:51]
	v_mfma_f32_16x16x32_bf16 v[48:51], v[148:151], v[180:183], v[48:51]
	v_mfma_f32_16x16x32_bf16 v[80:83], v[144:147], v[168:171], v[80:83]
	v_mfma_f32_16x16x32_bf16 v[80:83], v[148:151], v[172:175], v[80:83]
	s_setprio 0
	s_setprio 1
	s_waitcnt lgkmcnt(0)
	v_mfma_f32_16x16x32_bf16 v[76:79], v[152:155], v[168:171], v[76:79]
	v_mfma_f32_16x16x32_bf16 v[76:79], v[156:159], v[172:175], v[76:79]
	v_mfma_f32_16x16x32_bf16 v[44:47], v[152:155], v[176:179], v[44:47]
	v_mfma_f32_16x16x32_bf16 v[44:47], v[156:159], v[180:183], v[44:47]
	v_mfma_f32_16x16x32_bf16 v[20:23], v[152:155], v[184:187], v[20:23]
	v_mfma_f32_16x16x32_bf16 v[20:23], v[156:159], v[188:191], v[20:23]
	v_mfma_f32_16x16x32_bf16 v[4:7], v[152:155], v[192:195], v[4:7]
	v_mfma_f32_16x16x32_bf16 v[4:7], v[156:159], v[196:199], v[4:7]
	v_mfma_f32_16x16x32_bf16 v[0:3], v[160:163], v[192:195], v[0:3]
	v_mfma_f32_16x16x32_bf16 v[0:3], v[164:167], v[196:199], v[0:3]
	v_mfma_f32_16x16x32_bf16 v[16:19], v[160:163], v[184:187], v[16:19]
	v_mfma_f32_16x16x32_bf16 v[16:19], v[164:167], v[188:191], v[16:19]
	v_mfma_f32_16x16x32_bf16 v[32:35], v[160:163], v[176:179], v[32:35]
	v_mfma_f32_16x16x32_bf16 v[32:35], v[164:167], v[180:183], v[32:35]
	v_mfma_f32_16x16x32_bf16 v[64:67], v[160:163], v[168:171], v[64:67]
	s_barrier
	v_mfma_f32_16x16x32_bf16 v[64:67], v[164:167], v[172:175], v[64:67]
	s_setprio 0
	ds_read_b128 v[128:131], v141
	ds_read_b128 v[132:135], v141 offset:1024
	ds_read_b128 v[144:147], v141 offset:2048
	ds_read_b128 v[148:151], v141 offset:3072
	ds_read_b128 v[152:155], v142
	ds_read_b128 v[156:159], v142 offset:1024
	ds_read_b128 v[160:163], v142 offset:2048
	ds_read_b128 v[164:167], v142 offset:3072
	ds_read_b128 v[168:171], v140 offset:32768
	ds_read_b128 v[172:175], v140 offset:33792
	ds_read_b128 v[176:179], v140 offset:34816
	ds_read_b128 v[180:183], v140 offset:35840
	ds_read_b128 v[184:187], v140 offset:36864
	ds_read_b128 v[188:191], v140 offset:37888
	ds_read_b128 v[192:195], v140 offset:38912
	ds_read_b128 v[196:199], v140 offset:39936
	s_add_u32 s88, s46, 0x4000
	s_addc_u32 s89, s47, 0
	s_mov_b32 m0, s63
	s_nop 0
	global_load_lds_dwordx4 v136, s[88:89]
	s_add_u32 s88, s46, 0x6000
	s_addc_u32 s89, s47, 0
	s_mov_b32 m0, s64
	s_nop 0
	global_load_lds_dwordx4 v136, s[88:89]
	s_waitcnt vmcnt(8)
	s_waitcnt lgkmcnt(0)
	s_barrier
	s_setprio 1
	s_waitcnt lgkmcnt(7)
	s_waitcnt lgkmcnt(0)
	v_mfma_f32_16x16x32_bf16 v[120:123], v[128:131], v[168:171], v[120:123]
	v_mfma_f32_16x16x32_bf16 v[120:123], v[132:135], v[172:175], v[120:123]
	v_mfma_f32_16x16x32_bf16 v[104:107], v[128:131], v[176:179], v[104:107]
	v_mfma_f32_16x16x32_bf16 v[104:107], v[132:135], v[180:183], v[104:107]
	v_mfma_f32_16x16x32_bf16 v[84:87], v[128:131], v[184:187], v[84:87]
	v_mfma_f32_16x16x32_bf16 v[84:87], v[132:135], v[188:191], v[84:87]
	v_mfma_f32_16x16x32_bf16 v[52:55], v[128:131], v[192:195], v[52:55]
	v_mfma_f32_16x16x32_bf16 v[52:55], v[132:135], v[196:199], v[52:55]
	v_mfma_f32_16x16x32_bf16 v[36:39], v[144:147], v[192:195], v[36:39]
	v_mfma_f32_16x16x32_bf16 v[36:39], v[148:151], v[196:199], v[36:39]
	v_mfma_f32_16x16x32_bf16 v[68:71], v[144:147], v[184:187], v[68:71]
	v_mfma_f32_16x16x32_bf16 v[68:71], v[148:151], v[188:191], v[68:71]
	v_mfma_f32_16x16x32_bf16 v[96:99], v[144:147], v[176:179], v[96:99]
	v_mfma_f32_16x16x32_bf16 v[96:99], v[148:151], v[180:183], v[96:99]
	v_mfma_f32_16x16x32_bf16 v[112:115], v[144:147], v[168:171], v[112:115]
	v_mfma_f32_16x16x32_bf16 v[112:115], v[148:151], v[172:175], v[112:115]
	s_setprio 0
	s_setprio 1
	s_waitcnt lgkmcnt(0)
	v_mfma_f32_16x16x32_bf16 v[124:127], v[152:155], v[168:171], v[124:127]
	v_mfma_f32_16x16x32_bf16 v[124:127], v[156:159], v[172:175], v[124:127]
	v_mfma_f32_16x16x32_bf16 v[108:111], v[152:155], v[176:179], v[108:111]
	v_mfma_f32_16x16x32_bf16 v[108:111], v[156:159], v[180:183], v[108:111]
	v_mfma_f32_16x16x32_bf16 v[88:91], v[152:155], v[184:187], v[88:91]
	v_mfma_f32_16x16x32_bf16 v[88:91], v[156:159], v[188:191], v[88:91]
	v_mfma_f32_16x16x32_bf16 v[56:59], v[152:155], v[192:195], v[56:59]
	v_mfma_f32_16x16x32_bf16 v[56:59], v[156:159], v[196:199], v[56:59]
	v_mfma_f32_16x16x32_bf16 v[40:43], v[160:163], v[192:195], v[40:43]
	v_mfma_f32_16x16x32_bf16 v[40:43], v[164:167], v[196:199], v[40:43]
	v_mfma_f32_16x16x32_bf16 v[72:75], v[160:163], v[184:187], v[72:75]
	v_mfma_f32_16x16x32_bf16 v[72:75], v[164:167], v[188:191], v[72:75]
	v_mfma_f32_16x16x32_bf16 v[100:103], v[160:163], v[176:179], v[100:103]
	v_mfma_f32_16x16x32_bf16 v[100:103], v[164:167], v[180:183], v[100:103]
	v_mfma_f32_16x16x32_bf16 v[116:119], v[160:163], v[168:171], v[116:119]
	s_barrier
	v_mfma_f32_16x16x32_bf16 v[116:119], v[164:167], v[172:175], v[116:119]
	s_setprio 0
	ds_read_b128 v[168:171], v140 offset:49152
	ds_read_b128 v[172:175], v140 offset:50176
	ds_read_b128 v[176:179], v140 offset:51200
	ds_read_b128 v[180:183], v140 offset:52224
	ds_read_b128 v[184:187], v140 offset:53248
	ds_read_b128 v[188:191], v140 offset:54272
	ds_read_b128 v[192:195], v140 offset:55296
	ds_read_b128 v[196:199], v140 offset:56320
	s_mov_b32 m0, s68
	s_nop 0
	global_load_lds_dwordx4 v136, s[52:53]
	s_add_u32 s52, s56, 0xa000
	s_addc_u32 s53, s57, 0
	s_mov_b32 m0, s69
	s_nop 0
	global_load_lds_dwordx4 v136, s[52:53]
	s_add_u32 s52, s56, 0xc000
	s_addc_u32 s53, s57, 0
	s_mov_b32 m0, s72
	s_nop 0
	global_load_lds_dwordx4 v136, s[52:53]
	s_add_u32 s52, s56, 0xe000
	s_addc_u32 s53, s57, 0
	s_mov_b32 m0, s73
	s_nop 0
	global_load_lds_dwordx4 v136, s[52:53]
	s_add_u32 s46, s46, 0xa000
	s_mov_b32 m0, s70
	s_nop 0
	global_load_lds_dwordx4 v136, s[48:49]
	s_addc_u32 s47, s47, 0
	s_mov_b32 m0, s71
	s_nop 0
	global_load_lds_dwordx4 v136, s[46:47]
	s_waitcnt vmcnt(8)
	s_waitcnt lgkmcnt(0)
	s_barrier
	s_setprio 1
	s_waitcnt lgkmcnt(7)
	s_waitcnt lgkmcnt(0)
	v_mfma_f32_16x16x32_bf16 v[92:95], v[128:131], v[168:171], v[92:95]
	v_mfma_f32_16x16x32_bf16 v[92:95], v[132:135], v[172:175], v[92:95]
	v_mfma_f32_16x16x32_bf16 v[60:63], v[128:131], v[176:179], v[60:63]
	v_mfma_f32_16x16x32_bf16 v[60:63], v[132:135], v[180:183], v[60:63]
	v_mfma_f32_16x16x32_bf16 v[28:31], v[128:131], v[184:187], v[28:31]
	v_mfma_f32_16x16x32_bf16 v[28:31], v[132:135], v[188:191], v[28:31]
	v_mfma_f32_16x16x32_bf16 v[12:15], v[128:131], v[192:195], v[12:15]
	v_mfma_f32_16x16x32_bf16 v[12:15], v[132:135], v[196:199], v[12:15]
	v_mfma_f32_16x16x32_bf16 v[8:11], v[144:147], v[192:195], v[8:11]
	v_mfma_f32_16x16x32_bf16 v[8:11], v[148:151], v[196:199], v[8:11]
	v_mfma_f32_16x16x32_bf16 v[24:27], v[144:147], v[184:187], v[24:27]
	v_mfma_f32_16x16x32_bf16 v[24:27], v[148:151], v[188:191], v[24:27]
	v_mfma_f32_16x16x32_bf16 v[48:51], v[144:147], v[176:179], v[48:51]
	v_mfma_f32_16x16x32_bf16 v[48:51], v[148:151], v[180:183], v[48:51]
	v_mfma_f32_16x16x32_bf16 v[80:83], v[144:147], v[168:171], v[80:83]
	v_mfma_f32_16x16x32_bf16 v[80:83], v[148:151], v[172:175], v[80:83]
	s_setprio 0
	s_setprio 1
	s_waitcnt lgkmcnt(0)
	v_mfma_f32_16x16x32_bf16 v[76:79], v[152:155], v[168:171], v[76:79]
	v_mfma_f32_16x16x32_bf16 v[76:79], v[156:159], v[172:175], v[76:79]
	v_mfma_f32_16x16x32_bf16 v[44:47], v[152:155], v[176:179], v[44:47]
	v_mfma_f32_16x16x32_bf16 v[44:47], v[156:159], v[180:183], v[44:47]
	s_add_i32 s83, s83, 2
	v_mfma_f32_16x16x32_bf16 v[20:23], v[152:155], v[184:187], v[20:23]
	s_add_u32 s81, s81, 0x10000
	v_mfma_f32_16x16x32_bf16 v[20:23], v[156:159], v[188:191], v[20:23]
	s_addc_u32 s82, s82, 0
	v_mfma_f32_16x16x32_bf16 v[4:7], v[152:155], v[192:195], v[4:7]
	s_cmp_gt_u32 s83, 61
	v_mfma_f32_16x16x32_bf16 v[4:7], v[156:159], v[196:199], v[4:7]
	s_mov_b64 s[52:53], s[2:3]
	v_mfma_f32_16x16x32_bf16 v[0:3], v[160:163], v[192:195], v[0:3]
	v_mfma_f32_16x16x32_bf16 v[0:3], v[164:167], v[196:199], v[0:3]
	v_mfma_f32_16x16x32_bf16 v[16:19], v[160:163], v[184:187], v[16:19]
	v_mfma_f32_16x16x32_bf16 v[16:19], v[164:167], v[188:191], v[16:19]
	v_mfma_f32_16x16x32_bf16 v[32:35], v[160:163], v[176:179], v[32:35]
	v_mfma_f32_16x16x32_bf16 v[32:35], v[164:167], v[180:183], v[32:35]
	v_mfma_f32_16x16x32_bf16 v[64:67], v[160:163], v[168:171], v[64:67]
	s_barrier
	v_mfma_f32_16x16x32_bf16 v[64:67], v[164:167], v[172:175], v[64:67]
	s_setprio 0
	s_cbranch_scc0 .LBB0_1539
	s_nop 7
	s_and_b64 vcc, exec, s[8:9]
	s_cbranch_vccz .LBB0_1542
	s_barrier

.LBB0_1953:
	ds_read_b128 v[134:137], v128
	ds_read_b128 v[138:141], v128 offset:1024
	ds_read_b128 v[142:145], v128 offset:2048
	ds_read_b128 v[146:149], v128 offset:3072
	ds_read_b128 v[150:153], v129
	ds_read_b128 v[154:157], v129 offset:1024
	ds_read_b128 v[158:161], v129 offset:2048
	ds_read_b128 v[162:165], v129 offset:3072
	s_add_u32 s2, s28, 0x10000
	s_addc_u32 s3, s29, 0
	s_cmp_eq_u32 s77, 8
	s_cselect_b32 s38, s26, s2
	s_cselect_b32 s39, s27, s3
	s_cselect_b32 s42, s23, s75
	s_cselect_b32 s43, s25, s76
	s_add_u32 s40, s38, 0x8000
	s_addc_u32 s41, s39, 0
	ds_read_b128 v[166:169], v130
	ds_read_b128 v[170:173], v130 offset:1024
	ds_read_b128 v[174:177], v130 offset:2048
	ds_read_b128 v[178:181], v130 offset:3072
	ds_read_b128 v[182:185], v130 offset:4096
	ds_read_b128 v[192:195], v130 offset:5120
	ds_read_b128 v[196:199], v130 offset:6144
	ds_read_b128 v[200:203], v130 offset:7168
	s_add_u32 s78, s28, 0xc000
	s_addc_u32 s79, s29, 0
	s_mov_b32 m0, s63
	s_nop 0
	global_load_lds_dwordx4 v210, s[78:79]
	s_add_u32 s28, s28, 0xe000
	s_addc_u32 s29, s29, 0
	s_mov_b32 m0, s66
	s_nop 0
	global_load_lds_dwordx4 v210, s[28:29]
	s_waitcnt vmcnt(8)
	s_waitcnt lgkmcnt(0)
	s_barrier
	s_setprio 1
	s_waitcnt lgkmcnt(7)
	s_waitcnt lgkmcnt(0)
	v_mfma_f32_16x16x32_bf16 v[124:127], v[134:137], v[166:169], v[124:127]
	v_mfma_f32_16x16x32_bf16 v[124:127], v[138:141], v[170:173], v[124:127]
	v_mfma_f32_16x16x32_bf16 v[108:111], v[134:137], v[174:177], v[108:111]
	v_mfma_f32_16x16x32_bf16 v[108:111], v[138:141], v[178:181], v[108:111]
	v_mfma_f32_16x16x32_bf16 v[92:95], v[134:137], v[182:185], v[92:95]
	v_mfma_f32_16x16x32_bf16 v[92:95], v[138:141], v[192:195], v[92:95]
	v_mfma_f32_16x16x32_bf16 v[76:79], v[134:137], v[196:199], v[76:79]
	v_mfma_f32_16x16x32_bf16 v[76:79], v[138:141], v[200:203], v[76:79]
	v_mfma_f32_16x16x32_bf16 v[72:75], v[142:145], v[196:199], v[72:75]
	v_mfma_f32_16x16x32_bf16 v[72:75], v[146:149], v[200:203], v[72:75]
	v_mfma_f32_16x16x32_bf16 v[88:91], v[142:145], v[182:185], v[88:91]
	v_mfma_f32_16x16x32_bf16 v[88:91], v[146:149], v[192:195], v[88:91]
	v_mfma_f32_16x16x32_bf16 v[104:107], v[142:145], v[174:177], v[104:107]
	v_mfma_f32_16x16x32_bf16 v[104:107], v[146:149], v[178:181], v[104:107]
	v_mfma_f32_16x16x32_bf16 v[120:123], v[142:145], v[166:169], v[120:123]
	v_mfma_f32_16x16x32_bf16 v[120:123], v[146:149], v[170:173], v[120:123]
	s_setprio 0
	s_setprio 1
	s_waitcnt lgkmcnt(0)
	v_mfma_f32_16x16x32_bf16 v[116:119], v[150:153], v[166:169], v[116:119]
	v_mfma_f32_16x16x32_bf16 v[116:119], v[154:157], v[170:173], v[116:119]
	v_mfma_f32_16x16x32_bf16 v[100:103], v[150:153], v[174:177], v[100:103]
	v_mfma_f32_16x16x32_bf16 v[100:103], v[154:157], v[178:181], v[100:103]
	v_mfma_f32_16x16x32_bf16 v[84:87], v[150:153], v[182:185], v[84:87]
	v_mfma_f32_16x16x32_bf16 v[84:87], v[154:157], v[192:195], v[84:87]
	v_mfma_f32_16x16x32_bf16 v[68:71], v[150:153], v[196:199], v[68:71]
	v_mfma_f32_16x16x32_bf16 v[68:71], v[154:157], v[200:203], v[68:71]
	v_mfma_f32_16x16x32_bf16 v[64:67], v[158:161], v[196:199], v[64:67]
	v_mfma_f32_16x16x32_bf16 v[64:67], v[162:165], v[200:203], v[64:67]
	v_mfma_f32_16x16x32_bf16 v[80:83], v[158:161], v[182:185], v[80:83]
	v_mfma_f32_16x16x32_bf16 v[80:83], v[162:165], v[192:195], v[80:83]
	v_mfma_f32_16x16x32_bf16 v[96:99], v[158:161], v[174:177], v[96:99]
	v_mfma_f32_16x16x32_bf16 v[96:99], v[162:165], v[178:181], v[96:99]
	v_mfma_f32_16x16x32_bf16 v[112:115], v[158:161], v[166:169], v[112:115]
	s_barrier
	v_mfma_f32_16x16x32_bf16 v[112:115], v[162:165], v[170:173], v[112:115]
	s_setprio 0
	s_add_u32 s28, s42, 0x2000
	ds_read_b128 v[166:169], v130 offset:16384
	ds_read_b128 v[170:173], v130 offset:17408
	ds_read_b128 v[174:177], v130 offset:18432
	ds_read_b128 v[178:181], v130 offset:19456
	ds_read_b128 v[182:185], v130 offset:20480
	ds_read_b128 v[192:195], v130 offset:21504
	ds_read_b128 v[196:199], v130 offset:22528
	ds_read_b128 v[200:203], v130 offset:23552
	s_mov_b32 m0, s46
	s_nop 0
	global_load_lds_dwordx4 v210, s[42:43]
	s_addc_u32 s29, s43, 0
	s_mov_b32 m0, s47
	s_nop 0
	global_load_lds_dwordx4 v210, s[28:29]
	s_add_u32 s28, s42, 0x4000
	s_addc_u32 s29, s43, 0
	s_mov_b32 m0, s48
	s_nop 0
	global_load_lds_dwordx4 v210, s[28:29]
	s_add_u32 s28, s42, 0x6000
	s_addc_u32 s29, s43, 0
	s_mov_b32 m0, s49
	s_nop 0
	global_load_lds_dwordx4 v210, s[28:29]
	s_add_u32 s28, s38, 0x2000
	s_mov_b32 m0, s45
	s_nop 0
	global_load_lds_dwordx4 v210, s[38:39]
	s_addc_u32 s29, s39, 0
	s_mov_b32 m0, s50
	s_nop 0
	global_load_lds_dwordx4 v210, s[28:29]
	s_waitcnt vmcnt(8)
	s_waitcnt lgkmcnt(0)
	s_barrier
	s_setprio 1
	s_waitcnt lgkmcnt(7)
	s_waitcnt lgkmcnt(0)
	v_mfma_f32_16x16x32_bf16 v[60:63], v[134:137], v[166:169], v[60:63]
	v_mfma_f32_16x16x32_bf16 v[60:63], v[138:141], v[170:173], v[60:63]
	v_mfma_f32_16x16x32_bf16 v[44:47], v[134:137], v[174:177], v[44:47]
	v_mfma_f32_16x16x32_bf16 v[44:47], v[138:141], v[178:181], v[44:47]
	v_mfma_f32_16x16x32_bf16 v[28:31], v[134:137], v[182:185], v[28:31]
	v_mfma_f32_16x16x32_bf16 v[28:31], v[138:141], v[192:195], v[28:31]
	v_mfma_f32_16x16x32_bf16 v[12:15], v[134:137], v[196:199], v[12:15]
	v_mfma_f32_16x16x32_bf16 v[12:15], v[138:141], v[200:203], v[12:15]
	v_mfma_f32_16x16x32_bf16 v[8:11], v[142:145], v[196:199], v[8:11]
	v_mfma_f32_16x16x32_bf16 v[8:11], v[146:149], v[200:203], v[8:11]
	v_mfma_f32_16x16x32_bf16 v[24:27], v[142:145], v[182:185], v[24:27]
	v_mfma_f32_16x16x32_bf16 v[24:27], v[146:149], v[192:195], v[24:27]
	v_mfma_f32_16x16x32_bf16 v[40:43], v[142:145], v[174:177], v[40:43]
	v_mfma_f32_16x16x32_bf16 v[40:43], v[146:149], v[178:181], v[40:43]
	v_mfma_f32_16x16x32_bf16 v[56:59], v[142:145], v[166:169], v[56:59]
	v_mfma_f32_16x16x32_bf16 v[56:59], v[146:149], v[170:173], v[56:59]
	s_setprio 0
	s_setprio 1
	s_waitcnt lgkmcnt(0)
	v_mfma_f32_16x16x32_bf16 v[52:55], v[150:153], v[166:169], v[52:55]
	v_mfma_f32_16x16x32_bf16 v[52:55], v[154:157], v[170:173], v[52:55]
	v_mfma_f32_16x16x32_bf16 v[36:39], v[150:153], v[174:177], v[36:39]
	v_mfma_f32_16x16x32_bf16 v[36:39], v[154:157], v[178:181], v[36:39]
	v_mfma_f32_16x16x32_bf16 v[20:23], v[150:153], v[182:185], v[20:23]
	v_mfma_f32_16x16x32_bf16 v[20:23], v[154:157], v[192:195], v[20:23]
	v_mfma_f32_16x16x32_bf16 v[4:7], v[150:153], v[196:199], v[4:7]
	v_mfma_f32_16x16x32_bf16 v[4:7], v[154:157], v[200:203], v[4:7]
	v_mfma_f32_16x16x32_bf16 v[0:3], v[158:161], v[196:199], v[0:3]
	v_mfma_f32_16x16x32_bf16 v[0:3], v[162:165], v[200:203], v[0:3]
	v_mfma_f32_16x16x32_bf16 v[16:19], v[158:161], v[182:185], v[16:19]
	v_mfma_f32_16x16x32_bf16 v[16:19], v[162:165], v[192:195], v[16:19]
	v_mfma_f32_16x16x32_bf16 v[32:35], v[158:161], v[174:177], v[32:35]
	v_mfma_f32_16x16x32_bf16 v[32:35], v[162:165], v[178:181], v[32:35]
	v_mfma_f32_16x16x32_bf16 v[48:51], v[158:161], v[166:169], v[48:51]
	s_barrier
	v_mfma_f32_16x16x32_bf16 v[48:51], v[162:165], v[170:173], v[48:51]
	s_setprio 0
	ds_read_b128 v[134:137], v131
	ds_read_b128 v[138:141], v131 offset:1024
	ds_read_b128 v[142:145], v131 offset:2048
	ds_read_b128 v[146:149], v131 offset:3072
	ds_read_b128 v[150:153], v132
	ds_read_b128 v[154:157], v132 offset:1024
	ds_read_b128 v[158:161], v132 offset:2048
	ds_read_b128 v[162:165], v132 offset:3072
	ds_read_b128 v[166:169], v130 offset:32768
	ds_read_b128 v[170:173], v130 offset:33792
	ds_read_b128 v[174:177], v130 offset:34816
	ds_read_b128 v[178:181], v130 offset:35840
	ds_read_b128 v[182:185], v130 offset:36864
	ds_read_b128 v[192:195], v130 offset:37888
	ds_read_b128 v[196:199], v130 offset:38912
	ds_read_b128 v[200:203], v130 offset:39936
	s_add_u32 s28, s38, 0x4000
	s_addc_u32 s29, s39, 0
	s_mov_b32 m0, s51
	s_nop 0
	global_load_lds_dwordx4 v210, s[28:29]
	s_add_u32 s28, s38, 0x6000
	s_addc_u32 s29, s39, 0
	s_mov_b32 m0, s52
	s_nop 0
	global_load_lds_dwordx4 v210, s[28:29]
	s_waitcnt vmcnt(8)
	s_waitcnt lgkmcnt(0)
	s_barrier
	s_setprio 1
	s_waitcnt lgkmcnt(7)
	s_waitcnt lgkmcnt(0)
	v_mfma_f32_16x16x32_bf16 v[124:127], v[134:137], v[166:169], v[124:127]
	v_mfma_f32_16x16x32_bf16 v[124:127], v[138:141], v[170:173], v[124:127]
	v_mfma_f32_16x16x32_bf16 v[108:111], v[134:137], v[174:177], v[108:111]
	v_mfma_f32_16x16x32_bf16 v[108:111], v[138:141], v[178:181], v[108:111]
	v_mfma_f32_16x16x32_bf16 v[92:95], v[134:137], v[182:185], v[92:95]
	v_mfma_f32_16x16x32_bf16 v[92:95], v[138:141], v[192:195], v[92:95]
	v_mfma_f32_16x16x32_bf16 v[76:79], v[134:137], v[196:199], v[76:79]
	v_mfma_f32_16x16x32_bf16 v[76:79], v[138:141], v[200:203], v[76:79]
	v_mfma_f32_16x16x32_bf16 v[72:75], v[142:145], v[196:199], v[72:75]
	v_mfma_f32_16x16x32_bf16 v[72:75], v[146:149], v[200:203], v[72:75]
	v_mfma_f32_16x16x32_bf16 v[88:91], v[142:145], v[182:185], v[88:91]
	v_mfma_f32_16x16x32_bf16 v[88:91], v[146:149], v[192:195], v[88:91]
	v_mfma_f32_16x16x32_bf16 v[104:107], v[142:145], v[174:177], v[104:107]
	v_mfma_f32_16x16x32_bf16 v[104:107], v[146:149], v[178:181], v[104:107]
	v_mfma_f32_16x16x32_bf16 v[120:123], v[142:145], v[166:169], v[120:123]
	v_mfma_f32_16x16x32_bf16 v[120:123], v[146:149], v[170:173], v[120:123]
	s_setprio 0
	s_setprio 1
	s_waitcnt lgkmcnt(0)
	v_mfma_f32_16x16x32_bf16 v[116:119], v[150:153], v[166:169], v[116:119]
	v_mfma_f32_16x16x32_bf16 v[116:119], v[154:157], v[170:173], v[116:119]
	v_mfma_f32_16x16x32_bf16 v[100:103], v[150:153], v[174:177], v[100:103]
	v_mfma_f32_16x16x32_bf16 v[100:103], v[154:157], v[178:181], v[100:103]
	v_mfma_f32_16x16x32_bf16 v[84:87], v[150:153], v[182:185], v[84:87]
	v_mfma_f32_16x16x32_bf16 v[84:87], v[154:157], v[192:195], v[84:87]
	v_mfma_f32_16x16x32_bf16 v[68:71], v[150:153], v[196:199], v[68:71]
	v_mfma_f32_16x16x32_bf16 v[68:71], v[154:157], v[200:203], v[68:71]
	v_mfma_f32_16x16x32_bf16 v[64:67], v[158:161], v[196:199], v[64:67]
	v_mfma_f32_16x16x32_bf16 v[64:67], v[162:165], v[200:203], v[64:67]
	v_mfma_f32_16x16x32_bf16 v[80:83], v[158:161], v[182:185], v[80:83]
	v_mfma_f32_16x16x32_bf16 v[80:83], v[162:165], v[192:195], v[80:83]
	v_mfma_f32_16x16x32_bf16 v[96:99], v[158:161], v[174:177], v[96:99]
	v_mfma_f32_16x16x32_bf16 v[96:99], v[162:165], v[178:181], v[96:99]
	v_mfma_f32_16x16x32_bf16 v[112:115], v[158:161], v[166:169], v[112:115]
	s_barrier
	v_mfma_f32_16x16x32_bf16 v[112:115], v[162:165], v[170:173], v[112:115]
	s_setprio 0
	s_add_u32 s28, s42, 0x8000
	s_addc_u32 s29, s43, 0
	ds_read_b128 v[166:169], v130 offset:49152
	ds_read_b128 v[170:173], v130 offset:50176
	ds_read_b128 v[174:177], v130 offset:51200
	ds_read_b128 v[178:181], v130 offset:52224
	ds_read_b128 v[182:185], v130 offset:53248
	ds_read_b128 v[192:195], v130 offset:54272
	ds_read_b128 v[196:199], v130 offset:55296
	ds_read_b128 v[200:203], v130 offset:56320
	s_mov_b32 m0, s53
	s_nop 0
	global_load_lds_dwordx4 v210, s[28:29]
	s_add_u32 s28, s42, 0xa000
	s_addc_u32 s29, s43, 0
	s_mov_b32 m0, s54
	s_nop 0
	global_load_lds_dwordx4 v210, s[28:29]
	s_add_u32 s28, s42, 0xc000
	s_addc_u32 s29, s43, 0
	s_mov_b32 m0, s57
	s_nop 0
	global_load_lds_dwordx4 v210, s[28:29]
	s_add_u32 s28, s42, 0xe000
	s_addc_u32 s29, s43, 0
	s_mov_b32 m0, s58
	s_nop 0
	global_load_lds_dwordx4 v210, s[28:29]
	s_add_u32 s28, s38, 0xa000
	s_mov_b32 m0, s55
	s_nop 0
	global_load_lds_dwordx4 v210, s[40:41]
	s_addc_u32 s29, s39, 0
	s_mov_b32 m0, s56
	s_nop 0
	global_load_lds_dwordx4 v210, s[28:29]
	s_waitcnt vmcnt(8)
	s_waitcnt lgkmcnt(0)
	s_barrier
	s_setprio 1
	s_waitcnt lgkmcnt(7)
	s_waitcnt lgkmcnt(0)
	v_mfma_f32_16x16x32_bf16 v[60:63], v[134:137], v[166:169], v[60:63]
	v_mfma_f32_16x16x32_bf16 v[60:63], v[138:141], v[170:173], v[60:63]
	v_mfma_f32_16x16x32_bf16 v[44:47], v[134:137], v[174:177], v[44:47]
	v_mfma_f32_16x16x32_bf16 v[44:47], v[138:141], v[178:181], v[44:47]
	v_mfma_f32_16x16x32_bf16 v[28:31], v[134:137], v[182:185], v[28:31]
	v_mfma_f32_16x16x32_bf16 v[28:31], v[138:141], v[192:195], v[28:31]
	v_mfma_f32_16x16x32_bf16 v[12:15], v[134:137], v[196:199], v[12:15]
	v_mfma_f32_16x16x32_bf16 v[12:15], v[138:141], v[200:203], v[12:15]
	v_mfma_f32_16x16x32_bf16 v[8:11], v[142:145], v[196:199], v[8:11]
	v_mfma_f32_16x16x32_bf16 v[8:11], v[146:149], v[200:203], v[8:11]
	v_mfma_f32_16x16x32_bf16 v[24:27], v[142:145], v[182:185], v[24:27]
	v_mfma_f32_16x16x32_bf16 v[24:27], v[146:149], v[192:195], v[24:27]
	v_mfma_f32_16x16x32_bf16 v[40:43], v[142:145], v[174:177], v[40:43]
	v_mfma_f32_16x16x32_bf16 v[40:43], v[146:149], v[178:181], v[40:43]
	v_mfma_f32_16x16x32_bf16 v[56:59], v[142:145], v[166:169], v[56:59]
	v_mfma_f32_16x16x32_bf16 v[56:59], v[146:149], v[170:173], v[56:59]
	s_setprio 0
	s_setprio 1
	s_waitcnt lgkmcnt(0)
	v_mfma_f32_16x16x32_bf16 v[52:55], v[150:153], v[166:169], v[52:55]
	v_mfma_f32_16x16x32_bf16 v[52:55], v[154:157], v[170:173], v[52:55]
	v_mfma_f32_16x16x32_bf16 v[36:39], v[150:153], v[174:177], v[36:39]
	v_mfma_f32_16x16x32_bf16 v[36:39], v[154:157], v[178:181], v[36:39]
	s_add_i32 s77, s77, 2
	v_mfma_f32_16x16x32_bf16 v[20:23], v[150:153], v[182:185], v[20:23]
	s_add_u32 s75, s75, 0x10000
	v_mfma_f32_16x16x32_bf16 v[20:23], v[154:157], v[192:195], v[20:23]
	s_addc_u32 s76, s76, 0
	v_mfma_f32_16x16x32_bf16 v[4:7], v[150:153], v[196:199], v[4:7]
	s_cmp_gt_u32 s77, 9
	v_mfma_f32_16x16x32_bf16 v[4:7], v[154:157], v[200:203], v[4:7]
	s_mov_b64 s[28:29], s[2:3]
	v_mfma_f32_16x16x32_bf16 v[0:3], v[158:161], v[196:199], v[0:3]
	v_mfma_f32_16x16x32_bf16 v[0:3], v[162:165], v[200:203], v[0:3]
	v_mfma_f32_16x16x32_bf16 v[16:19], v[158:161], v[182:185], v[16:19]
	v_mfma_f32_16x16x32_bf16 v[16:19], v[162:165], v[192:195], v[16:19]
	v_mfma_f32_16x16x32_bf16 v[32:35], v[158:161], v[174:177], v[32:35]
	v_mfma_f32_16x16x32_bf16 v[32:35], v[162:165], v[178:181], v[32:35]
	v_mfma_f32_16x16x32_bf16 v[48:51], v[158:161], v[166:169], v[48:51]
	s_barrier
	v_mfma_f32_16x16x32_bf16 v[48:51], v[162:165], v[170:173], v[48:51]
	s_setprio 0
	s_cbranch_scc0 .LBB0_1953
	s_nop 7
	v_mbcnt_lo_u32_b32 v128, -1, 0
	v_mbcnt_hi_u32_b32 v128, -1, v128
	s_add_u32 s19, s69, s19
	v_lshlrev_b32_e32 v128, 4, v128
	v_add_u32_e32 v129, s60, v128
	v_add_u32_e32 v128, s62, v128
	s_addc_u32 s17, s70, s17
	s_mov_b32 s23, -2
	v_add_u32_e32 v128, 0, v128
	v_add_u32_e32 v129, 0, v129
